# RoPE epilogue stores widened: v_permlane16_swap between neighbouring 16-lane rows, one 16-byte store per row group instead of two 8-byte stores
# speedup vs baseline: 1.0021x; 1.0021x over previous
.LBB0_461:
	v_mov_b32_e32 v12, v21
	v_mov_b32_e32 v13, v25
	v_pk_mul_f32 v[12:13], v[12:13], v[8:9]
	s_and_b64 vcc, exec, s[6:7]
	v_add_f32_e32 v14, v12, v13
	v_mov_b32_e32 v12, v25
	v_mov_b32_e32 v13, v21
	v_pk_mul_f32 v[8:9], v[12:13], v[8:9]
	v_mov_b32_e32 v21, v24
	v_mov_b32_e32 v25, v20
	v_sub_f32_e32 v12, v8, v9
	v_pk_mul_f32 v[8:9], v[20:21], v[6:7]
	v_pk_mul_f32 v[6:7], v[24:25], v[6:7]
	v_add_f32_e32 v8, v8, v9
	v_sub_f32_e32 v9, v6, v7
	v_mov_b32_e32 v6, v19
	v_mov_b32_e32 v7, v23
	v_pk_mul_f32 v[6:7], v[6:7], v[4:5]
	s_mov_b32 s8, s22
	v_add_f32_e32 v13, v6, v7
	v_mov_b32_e32 v6, v23
	v_mov_b32_e32 v7, v19
	v_pk_mul_f32 v[4:5], v[6:7], v[4:5]
	v_mov_b32_e32 v19, v22
	v_mov_b32_e32 v23, v18
	v_sub_f32_e32 v6, v4, v5
	v_pk_mul_f32 v[4:5], v[18:19], v[2:3]
	v_pk_mul_f32 v[2:3], v[22:23], v[2:3]
	v_add_f32_e32 v4, v4, v5
	v_sub_f32_e32 v2, v2, v3
	v_cvt_pk_bf16_f32 v2, v2, v6
	v_cvt_pk_bf16_f32 v3, v9, v12
	v_cvt_pk_bf16_f32 v4, v4, v13
	v_cvt_pk_bf16_f32 v5, v8, v14
	s_nop 1
	v_permlane16_swap_b32 v2, v4
	v_permlane16_swap_b32 v3, v5
	v_lshl_add_u64 v[206:207], v[10:11], 0, v[204:205]
	global_store_dwordx4 v[206:207], v[2:5], off
	s_mov_b32 s10, s24
	s_mov_b64 s[34:35], s[28:29]
	s_mov_b64 s[30:31], s[26:27]
	s_cbranch_vccnz .LBB0_546

.LBB0_465:
	ds_read_b128 v[2:5], v175
	ds_read_b128 v[6:9], v176
	ds_read_b128 v[10:13], v177
	ds_read_b128 v[14:17], v178
	s_add_u32 s34, s30, 0xfffc0080
	s_addc_u32 s35, s31, -1
	s_cmp_eq_u32 s68, 12
	s_cselect_b32 s37, s9, s35
	s_cselect_b32 s36, s11, s34
	s_cselect_b32 s35, s23, s67
	s_cselect_b32 s34, s25, s66
	v_lshl_add_u64 v[164:165], s[30:31], 0, v[156:157]
	s_add_i32 m0, s45, 0xc000
	ds_read_b128 v[194:197], v191
	ds_read_b128 v[198:201], v191 offset:1024
	ds_read_b128 v[202:205], v191 offset:2048
	ds_read_b128 v[206:209], v191 offset:3072
	ds_read_b128 v[216:219], v191 offset:4096
	ds_read_b128 v[220:223], v191 offset:5120
	ds_read_b128 v[224:227], v191 offset:6144
	ds_read_b128 v[228:231], v191 offset:7168
	global_load_lds_dwordx4 v[164:165], off
	v_lshl_add_u64 v[164:165], s[30:31], 0, v[158:159]
	s_add_i32 m0, s45, 0xe000
	s_nop 0
	global_load_lds_dwordx4 v[164:165], off
	s_waitcnt lgkmcnt(8)
	s_barrier
	s_waitcnt lgkmcnt(0)
	s_setprio 1
	s_waitcnt lgkmcnt(0)
	v_mfma_scale_f32_16x16x128_f8f6f4 v[142:145], v[2:9], v[194:201], v[142:145], v192, v192 op_sel_hi:[0,0,0]
	v_mfma_scale_f32_16x16x128_f8f6f4 v[138:141], v[10:17], v[194:201], v[138:141], v192, v192 op_sel_hi:[0,0,0]
	v_mfma_scale_f32_16x16x128_f8f6f4 v[126:129], v[2:9], v[202:209], v[126:129], v192, v192 op_sel_hi:[0,0,0]
	v_mfma_scale_f32_16x16x128_f8f6f4 v[122:125], v[10:17], v[202:209], v[122:125], v192, v192 op_sel_hi:[0,0,0]
	v_mfma_scale_f32_16x16x128_f8f6f4 v[110:113], v[2:9], v[216:223], v[110:113], v192, v192 op_sel_hi:[0,0,0]
	v_mfma_scale_f32_16x16x128_f8f6f4 v[106:109], v[10:17], v[216:223], v[106:109], v192, v192 op_sel_hi:[0,0,0]
	v_mfma_scale_f32_16x16x128_f8f6f4 v[94:97], v[2:9], v[224:231], v[94:97], v192, v192 op_sel_hi:[0,0,0]
	v_mfma_scale_f32_16x16x128_f8f6f4 v[90:93], v[10:17], v[224:231], v[90:93], v192, v192 op_sel_hi:[0,0,0]
	s_setprio 0
	s_barrier
	s_mov_b32 m0, s46
	v_lshl_add_u64 v[164:165], s[34:35], 0, v[146:147]
	ds_read_b128 v[232:235], v179
	ds_read_b128 v[236:239], v180
	ds_read_b128 v[240:243], v181
	ds_read_b128 v[244:247], v182
	global_load_lds_dwordx4 v[164:165], off
	v_lshl_add_u64 v[166:167], s[34:35], 0, v[148:149]
	s_mov_b32 m0, s47
	s_nop 0
	global_load_lds_dwordx4 v[166:167], off
	s_barrier
	s_waitcnt lgkmcnt(0)
	s_setprio 1
	s_waitcnt lgkmcnt(0)
	v_mfma_scale_f32_16x16x128_f8f6f4 v[134:137], v[232:239], v[194:201], v[134:137], v192, v192 op_sel_hi:[0,0,0]
	v_mfma_scale_f32_16x16x128_f8f6f4 v[130:133], v[240:247], v[194:201], v[130:133], v192, v192 op_sel_hi:[0,0,0]
	v_mfma_scale_f32_16x16x128_f8f6f4 v[118:121], v[232:239], v[202:209], v[118:121], v192, v192 op_sel_hi:[0,0,0]
	v_mfma_scale_f32_16x16x128_f8f6f4 v[114:117], v[240:247], v[202:209], v[114:117], v192, v192 op_sel_hi:[0,0,0]
	v_mfma_scale_f32_16x16x128_f8f6f4 v[102:105], v[232:239], v[216:223], v[102:105], v192, v192 op_sel_hi:[0,0,0]
	v_mfma_scale_f32_16x16x128_f8f6f4 v[98:101], v[240:247], v[216:223], v[98:101], v192, v192 op_sel_hi:[0,0,0]
	v_mfma_scale_f32_16x16x128_f8f6f4 v[86:89], v[232:239], v[224:231], v[86:89], v192, v192 op_sel_hi:[0,0,0]
	v_mfma_scale_f32_16x16x128_f8f6f4 v[82:85], v[240:247], v[224:231], v[82:85], v192, v192 op_sel_hi:[0,0,0]
	s_setprio 0
	s_mov_b32 m0, s45
	v_lshl_add_u64 v[168:169], s[36:37], 0, v[146:147]
	s_barrier
	ds_read_b128 v[194:197], v191 offset:16384
	ds_read_b128 v[198:201], v191 offset:17408
	ds_read_b128 v[202:205], v191 offset:18432
	ds_read_b128 v[206:209], v191 offset:19456
	ds_read_b128 v[216:219], v191 offset:20480
	ds_read_b128 v[220:223], v191 offset:21504
	ds_read_b128 v[224:227], v191 offset:22528
	ds_read_b128 v[228:231], v191 offset:23552
	global_load_lds_dwordx4 v[168:169], off
	v_lshl_add_u64 v[170:171], s[36:37], 0, v[148:149]
	s_mov_b32 m0, s50
	s_nop 0
	global_load_lds_dwordx4 v[170:171], off
	s_barrier
	s_waitcnt lgkmcnt(0)
	s_setprio 1
	s_waitcnt lgkmcnt(0)
	v_mfma_scale_f32_16x16x128_f8f6f4 v[78:81], v[2:9], v[194:201], v[78:81], v192, v192 op_sel_hi:[0,0,0]
	v_mfma_scale_f32_16x16x128_f8f6f4 v[74:77], v[10:17], v[194:201], v[74:77], v192, v192 op_sel_hi:[0,0,0]
	v_mfma_scale_f32_16x16x128_f8f6f4 v[62:65], v[2:9], v[202:209], v[62:65], v192, v192 op_sel_hi:[0,0,0]
	v_mfma_scale_f32_16x16x128_f8f6f4 v[58:61], v[10:17], v[202:209], v[58:61], v192, v192 op_sel_hi:[0,0,0]
	v_mfma_scale_f32_16x16x128_f8f6f4 v[46:49], v[2:9], v[216:223], v[46:49], v192, v192 op_sel_hi:[0,0,0]
	v_mfma_scale_f32_16x16x128_f8f6f4 v[42:45], v[10:17], v[216:223], v[42:45], v192, v192 op_sel_hi:[0,0,0]
	v_mfma_scale_f32_16x16x128_f8f6f4 v[30:33], v[2:9], v[224:231], v[30:33], v192, v192 op_sel_hi:[0,0,0]
	v_mfma_scale_f32_16x16x128_f8f6f4 v[26:29], v[10:17], v[224:231], v[26:29], v192, v192 op_sel_hi:[0,0,0]
	s_setprio 0
	s_barrier
	s_add_u32 s70, s34, 0x40000
	s_addc_u32 s71, s35, 0
	s_mov_b32 m0, s51
	v_lshl_add_u64 v[2:3], s[70:71], 0, v[146:147]
	global_load_lds_dwordx4 v[2:3], off
	v_lshl_add_u64 v[2:3], s[70:71], 0, v[148:149]
	s_mov_b32 m0, s52
	s_nop 0
	global_load_lds_dwordx4 v[2:3], off
	s_waitcnt vmcnt(6)
	s_barrier
	s_setprio 1
	v_mfma_scale_f32_16x16x128_f8f6f4 v[70:73], v[232:239], v[194:201], v[70:73], v192, v192 op_sel_hi:[0,0,0]
	v_mfma_scale_f32_16x16x128_f8f6f4 v[66:69], v[240:247], v[194:201], v[66:69], v192, v192 op_sel_hi:[0,0,0]
	v_mfma_scale_f32_16x16x128_f8f6f4 v[54:57], v[232:239], v[202:209], v[54:57], v192, v192 op_sel_hi:[0,0,0]
	v_mfma_scale_f32_16x16x128_f8f6f4 v[50:53], v[240:247], v[202:209], v[50:53], v192, v192 op_sel_hi:[0,0,0]
	v_mfma_scale_f32_16x16x128_f8f6f4 v[38:41], v[232:239], v[216:223], v[38:41], v192, v192 op_sel_hi:[0,0,0]
	v_mfma_scale_f32_16x16x128_f8f6f4 v[34:37], v[240:247], v[216:223], v[34:37], v192, v192 op_sel_hi:[0,0,0]
	v_mfma_scale_f32_16x16x128_f8f6f4 v[22:25], v[232:239], v[224:231], v[22:25], v192, v192 op_sel_hi:[0,0,0]
	v_mfma_scale_f32_16x16x128_f8f6f4 v[18:21], v[240:247], v[224:231], v[18:21], v192, v192 op_sel_hi:[0,0,0]
	s_setprio 0
	s_barrier
	ds_read_b128 v[2:5], v183
	ds_read_b128 v[6:9], v184
	ds_read_b128 v[10:13], v185
	ds_read_b128 v[14:17], v186
	s_add_u32 s36, s36, 0x40000
	s_addc_u32 s37, s37, 0
	s_mov_b32 m0, s53
	v_lshl_add_u64 v[210:211], s[36:37], 0, v[146:147]
	ds_read_b128 v[194:197], v191 offset:32768
	ds_read_b128 v[198:201], v191 offset:33792
	ds_read_b128 v[202:205], v191 offset:34816
	ds_read_b128 v[206:209], v191 offset:35840
	ds_read_b128 v[216:219], v191 offset:36864
	ds_read_b128 v[220:223], v191 offset:37888
	ds_read_b128 v[224:227], v191 offset:38912
	ds_read_b128 v[228:231], v191 offset:39936
	global_load_lds_dwordx4 v[210:211], off
	v_lshl_add_u64 v[210:211], s[36:37], 0, v[148:149]
	s_mov_b32 m0, s54
	s_nop 0
	global_load_lds_dwordx4 v[210:211], off
	s_waitcnt lgkmcnt(8)
	s_barrier
	s_waitcnt lgkmcnt(0)
	s_setprio 1
	s_waitcnt lgkmcnt(0)
	v_mfma_scale_f32_16x16x128_f8f6f4 v[142:145], v[2:9], v[194:201], v[142:145], v192, v192 op_sel_hi:[0,0,0]
	v_mfma_scale_f32_16x16x128_f8f6f4 v[138:141], v[10:17], v[194:201], v[138:141], v192, v192 op_sel_hi:[0,0,0]
	v_mfma_scale_f32_16x16x128_f8f6f4 v[126:129], v[2:9], v[202:209], v[126:129], v192, v192 op_sel_hi:[0,0,0]
	v_mfma_scale_f32_16x16x128_f8f6f4 v[122:125], v[10:17], v[202:209], v[122:125], v192, v192 op_sel_hi:[0,0,0]
	v_mfma_scale_f32_16x16x128_f8f6f4 v[110:113], v[2:9], v[216:223], v[110:113], v192, v192 op_sel_hi:[0,0,0]
	v_mfma_scale_f32_16x16x128_f8f6f4 v[106:109], v[10:17], v[216:223], v[106:109], v192, v192 op_sel_hi:[0,0,0]
	v_mfma_scale_f32_16x16x128_f8f6f4 v[94:97], v[2:9], v[224:231], v[94:97], v192, v192 op_sel_hi:[0,0,0]
	v_mfma_scale_f32_16x16x128_f8f6f4 v[90:93], v[10:17], v[224:231], v[90:93], v192, v192 op_sel_hi:[0,0,0]
	s_setprio 0
	s_barrier
	s_mov_b32 m0, s58
	v_lshl_add_u64 v[164:165], v[164:165], 0, s[14:15]
	ds_read_b128 v[232:235], v187
	ds_read_b128 v[236:239], v188
	ds_read_b128 v[240:243], v189
	ds_read_b128 v[244:247], v190
	global_load_lds_dwordx4 v[164:165], off
	v_lshl_add_u64 v[164:165], v[166:167], 0, s[14:15]
	s_mov_b32 m0, s59
	s_nop 0
	global_load_lds_dwordx4 v[164:165], off
	s_barrier
	s_waitcnt lgkmcnt(0)
	s_setprio 1
	s_waitcnt lgkmcnt(0)
	v_mfma_scale_f32_16x16x128_f8f6f4 v[134:137], v[232:239], v[194:201], v[134:137], v192, v192 op_sel_hi:[0,0,0]
	v_mfma_scale_f32_16x16x128_f8f6f4 v[130:133], v[240:247], v[194:201], v[130:133], v192, v192 op_sel_hi:[0,0,0]
	v_mfma_scale_f32_16x16x128_f8f6f4 v[118:121], v[232:239], v[202:209], v[118:121], v192, v192 op_sel_hi:[0,0,0]
	v_mfma_scale_f32_16x16x128_f8f6f4 v[114:117], v[240:247], v[202:209], v[114:117], v192, v192 op_sel_hi:[0,0,0]
	v_mfma_scale_f32_16x16x128_f8f6f4 v[102:105], v[232:239], v[216:223], v[102:105], v192, v192 op_sel_hi:[0,0,0]
	v_mfma_scale_f32_16x16x128_f8f6f4 v[98:101], v[240:247], v[216:223], v[98:101], v192, v192 op_sel_hi:[0,0,0]
	v_mfma_scale_f32_16x16x128_f8f6f4 v[86:89], v[232:239], v[224:231], v[86:89], v192, v192 op_sel_hi:[0,0,0]
	v_mfma_scale_f32_16x16x128_f8f6f4 v[82:85], v[240:247], v[224:231], v[82:85], v192, v192 op_sel_hi:[0,0,0]
	s_setprio 0
	s_mov_b32 m0, s60
	v_lshl_add_u64 v[164:165], v[168:169], 0, s[14:15]
	s_barrier
	ds_read_b128 v[194:197], v191 offset:49152
	ds_read_b128 v[198:201], v191 offset:50176
	ds_read_b128 v[202:205], v191 offset:51200
	ds_read_b128 v[206:209], v191 offset:52224
	ds_read_b128 v[216:219], v191 offset:53248
	ds_read_b128 v[220:223], v191 offset:54272
	ds_read_b128 v[224:227], v191 offset:55296
	ds_read_b128 v[228:231], v191 offset:56320
	global_load_lds_dwordx4 v[164:165], off
	v_lshl_add_u64 v[164:165], v[170:171], 0, s[14:15]
	s_mov_b32 m0, s61
	s_nop 0
	global_load_lds_dwordx4 v[164:165], off
	s_barrier
	s_waitcnt lgkmcnt(0)
	s_setprio 1
	s_waitcnt lgkmcnt(0)
	v_mfma_scale_f32_16x16x128_f8f6f4 v[78:81], v[2:9], v[194:201], v[78:81], v192, v192 op_sel_hi:[0,0,0]
	v_mfma_scale_f32_16x16x128_f8f6f4 v[74:77], v[10:17], v[194:201], v[74:77], v192, v192 op_sel_hi:[0,0,0]
	v_mfma_scale_f32_16x16x128_f8f6f4 v[62:65], v[2:9], v[202:209], v[62:65], v192, v192 op_sel_hi:[0,0,0]
	v_mfma_scale_f32_16x16x128_f8f6f4 v[58:61], v[10:17], v[202:209], v[58:61], v192, v192 op_sel_hi:[0,0,0]
	v_mfma_scale_f32_16x16x128_f8f6f4 v[46:49], v[2:9], v[216:223], v[46:49], v192, v192 op_sel_hi:[0,0,0]
	v_mfma_scale_f32_16x16x128_f8f6f4 v[42:45], v[10:17], v[216:223], v[42:45], v192, v192 op_sel_hi:[0,0,0]
	v_mfma_scale_f32_16x16x128_f8f6f4 v[30:33], v[2:9], v[224:231], v[30:33], v192, v192 op_sel_hi:[0,0,0]
	v_mfma_scale_f32_16x16x128_f8f6f4 v[26:29], v[10:17], v[224:231], v[26:29], v192, v192 op_sel_hi:[0,0,0]
	s_setprio 0
	s_barrier
	s_add_u32 s34, s34, 0x40080
	s_addc_u32 s35, s35, 0
	s_mov_b32 m0, s62
	v_lshl_add_u64 v[2:3], s[34:35], 0, v[146:147]
	global_load_lds_dwordx4 v[2:3], off
	v_lshl_add_u64 v[2:3], s[34:35], 0, v[148:149]
	s_mov_b32 m0, s63
	s_nop 0
	global_load_lds_dwordx4 v[2:3], off
	s_waitcnt vmcnt(6)
	s_barrier
	s_setprio 1
	v_mfma_scale_f32_16x16x128_f8f6f4 v[70:73], v[232:239], v[194:201], v[70:73], v192, v192 op_sel_hi:[0,0,0]
	v_mfma_scale_f32_16x16x128_f8f6f4 v[66:69], v[240:247], v[194:201], v[66:69], v192, v192 op_sel_hi:[0,0,0]
	v_mfma_scale_f32_16x16x128_f8f6f4 v[54:57], v[232:239], v[202:209], v[54:57], v192, v192 op_sel_hi:[0,0,0]
	v_mfma_scale_f32_16x16x128_f8f6f4 v[50:53], v[240:247], v[202:209], v[50:53], v192, v192 op_sel_hi:[0,0,0]
	v_mfma_scale_f32_16x16x128_f8f6f4 v[38:41], v[232:239], v[216:223], v[38:41], v192, v192 op_sel_hi:[0,0,0]
	v_mfma_scale_f32_16x16x128_f8f6f4 v[34:37], v[240:247], v[216:223], v[34:37], v192, v192 op_sel_hi:[0,0,0]
	v_mfma_scale_f32_16x16x128_f8f6f4 v[22:25], v[232:239], v[224:231], v[22:25], v192, v192 op_sel_hi:[0,0,0]
	v_mfma_scale_f32_16x16x128_f8f6f4 v[18:21], v[240:247], v[224:231], v[18:21], v192, v192 op_sel_hi:[0,0,0]
	s_setprio 0
	s_add_i32 s68, s68, 2
	s_add_u32 s30, s30, 0x100
	s_addc_u32 s31, s31, 0
	s_add_u32 s66, s66, 0x100
	s_addc_u32 s67, s67, 0
	s_cmp_gt_u32 s68, 13
	s_barrier
	s_cbranch_scc0 .LBB0_465
	s_lshl_b32 s23, s10, 8
	s_nop 15
	s_nop 15
	s_add_i32 s23, s23, s57
	v_mbcnt_lo_u32_b32 v204, -1, 0
	v_mbcnt_hi_u32_b32 v204, -1, v204
	v_bfe_u32 v204, v204, 4, 1
	v_mul_u32_u24_e32 v204, 24, v204
	v_mov_b32_e32 v205, 0
	v_or_b32_e32 v12, s23, v1
	v_cmp_gt_i32_e32 vcc, s56, v12
	v_mov_b32_e32 v3, 0
	v_mov_b32_e32 v2, 1.0
	v_mov_b32_e32 v4, 1.0
	v_mov_b32_e32 v5, 0
	v_mov_b32_e32 v6, 1.0
	v_mov_b32_e32 v7, 0
	v_mov_b32_e32 v8, 1.0
	v_mov_b32_e32 v9, 0
	s_and_saveexec_b64 s[10:11], vcc
	s_cbranch_execz .LBB0_468
	s_bfe_u32 s9, s23, 0x50006
	v_mov_b32_e32 v2, s9
	v_cndmask_b32_e64 v2, v1, v2, s[4:5]
	v_lshlrev_b32_e32 v150, 8, v2
	v_lshl_add_u64 v[6:7], v[154:155], 0, v[150:151]
	global_load_dwordx4 v[2:5], v[6:7], off offset:16
	s_nop 0
	global_load_dwordx4 v[6:9], v[6:7], off

.Lrope_a_1:
	s_or_b64 exec, exec, s[98:99]
	v_mul_f32_e32 v150, v138, v7
	v_fma_f32 v150, v142, v6, -v150
	v_mul_f32_e32 v142, v142, v7
	v_fmac_f32_e32 v142, v138, v6
	v_mul_f32_e32 v138, v139, v9
	v_fma_f32 v138, v143, v8, -v138
	v_mul_f32_e32 v143, v143, v9
	v_fmac_f32_e32 v143, v139, v8
	v_mul_f32_e32 v139, v140, v3
	v_fma_f32 v139, v144, v2, -v139
	v_mul_f32_e32 v144, v144, v3
	s_or_b32 s25, s30, 0x80
	v_fmac_f32_e32 v144, v140, v2
	v_mul_f32_e32 v140, v141, v5
	s_cmpk_gt_i32 s25, 0x7ff
	v_fma_f32 v140, v145, v4, -v140
	v_mul_f32_e32 v145, v145, v5
	v_cvt_pk_bf16_f32 v138, v150, v138
	v_cvt_pk_bf16_f32 v139, v139, v140
	s_mov_b64 s[8:9], -1
	s_cselect_b64 s[34:35], -1, 0
	s_cmpk_lt_i32 s25, 0x800
	v_add_u32_e32 v150, s30, v152
	v_fmac_f32_e32 v145, v141, v4
	v_cvt_pk_bf16_f32 v140, v142, v143
	v_cvt_pk_bf16_f32 v141, v144, v145
	s_nop 1
	v_permlane16_swap_b32 v138, v140
	v_permlane16_swap_b32 v139, v141
	v_lshl_add_u64 v[206:207], v[16:17], 0, v[204:205]
	global_store_dwordx4 v[206:207], v[138:141], off
	s_cbranch_scc1 .LBB0_474
	v_lshl_add_u64 v[14:15], v[150:151], 1, v[14:15]
	v_lshl_add_u64 v[16:17], v[14:15], 0, s[20:21]
	s_mov_b64 s[8:9], 0

.LBB0_476:
	v_mul_f32_e32 v12, v130, v7
	v_mul_f32_e32 v7, v134, v7
	v_fma_f32 v12, v134, v6, -v12
	v_fmac_f32_e32 v7, v130, v6
	v_mul_f32_e32 v6, v131, v9
	v_mul_f32_e32 v9, v135, v9
	v_fma_f32 v6, v135, v8, -v6
	v_fmac_f32_e32 v9, v131, v8
	v_mul_f32_e32 v8, v132, v3
	v_mul_f32_e32 v13, v136, v3
	v_fma_f32 v8, v136, v2, -v8
	v_fmac_f32_e32 v13, v132, v2
	v_mul_f32_e32 v2, v133, v5
	v_fma_f32 v3, v137, v4, -v2
	v_mul_f32_e32 v5, v137, v5
	v_fmac_f32_e32 v5, v133, v4
	v_cvt_pk_bf16_f32 v2, v12, v6
	v_cvt_pk_bf16_f32 v3, v8, v3
	v_cvt_pk_bf16_f32 v4, v7, v9
	v_cvt_pk_bf16_f32 v5, v13, v5
	s_nop 1
	v_permlane16_swap_b32 v2, v4
	v_permlane16_swap_b32 v3, v5
	v_lshl_add_u64 v[206:207], v[16:17], 0, v[204:205]
	global_store_dwordx4 v[206:207], v[2:5], off
	v_or_b32_e32 v12, s23, v172
	v_ashrrev_i32_e32 v13, 31, v12
	v_lshlrev_b64 v[14:15], 10, v[12:13]
	v_cndmask_b32_e64 v16, 0, 1, s[10:11]
	s_mov_b64 s[36:37], -1
	v_cmp_ne_u32_e64 s[8:9], 1, v16
	s_andn2_b64 vcc, exec, s[10:11]
	v_lshl_add_u64 v[14:15], s[12:13], 0, v[14:15]
	s_cbranch_vccnz .LBB0_480
	v_mov_b32_e32 v16, v10
	v_mov_b32_e32 v17, v151
	v_lshl_add_u64 v[16:17], v[16:17], 1, v[14:15]
	v_lshl_add_u64 v[16:17], v[16:17], 0, s[18:19]
	s_mov_b64 s[36:37], 0

.LBB0_482:
	s_waitcnt vmcnt(2)
	v_or_b32_e32 v202, s23, v173
	v_cmp_gt_i32_e32 vcc, s56, v202
	v_mov_b32_e32 v3, 0
	v_mov_b32_e32 v2, 1.0
	v_mov_b32_e32 v4, 1.0
	v_mov_b32_e32 v5, 0
	v_mov_b32_e32 v6, 1.0
	v_mov_b32_e32 v7, 0
	v_mov_b32_e32 v8, 1.0
	v_mov_b32_e32 v9, 0
	s_and_saveexec_b64 s[98:99], vcc
	s_cbranch_execz .Lrope_a_2
	s_bfe_u32 s25, s23, 0x50006
	v_mov_b32_e32 v2, s25
	v_cndmask_b32_e64 v2, v173, v2, s[4:5]
	v_lshlrev_b32_e32 v2, 8, v2
	v_mov_b32_e32 v3, v151
	v_lshl_add_u64 v[6:7], v[154:155], 0, v[2:3]
	global_load_dwordx4 v[2:5], v[6:7], off offset:16
	s_nop 0
	global_load_dwordx4 v[6:9], v[6:7], off
.Lrope_a_2:
	s_or_b64 exec, exec, s[98:99]
	v_mul_f32_e32 v130, v122, v199
	v_fma_f32 v130, v126, v198, -v130
	v_mul_f32_e32 v126, v126, v199
	v_fmac_f32_e32 v126, v122, v198
	v_mul_f32_e32 v122, v123, v201
	v_fma_f32 v122, v127, v200, -v122
	v_mul_f32_e32 v127, v127, v201
	v_fmac_f32_e32 v127, v123, v200
	v_mul_f32_e32 v123, v124, v195
	v_fma_f32 v123, v128, v194, -v123
	v_mul_f32_e32 v128, v128, v195
	v_fmac_f32_e32 v128, v124, v194
	v_mul_f32_e32 v124, v125, v197
	v_fma_f32 v124, v129, v196, -v124
	v_mul_f32_e32 v129, v129, v197
	v_cvt_pk_bf16_f32 v122, v130, v122
	v_cvt_pk_bf16_f32 v123, v123, v124
	v_fmac_f32_e32 v129, v125, v196
	v_cvt_pk_bf16_f32 v124, v126, v127
	v_cvt_pk_bf16_f32 v125, v128, v129
	s_nop 1
	v_permlane16_swap_b32 v122, v124
	v_permlane16_swap_b32 v123, v125
	v_lshl_add_u64 v[206:207], v[16:17], 0, v[204:205]
	global_store_dwordx4 v[206:207], v[122:125], off
	v_cndmask_b32_e64 v16, 0, 1, s[34:35]
	v_cmp_ne_u32_e64 s[10:11], 1, v16
	s_andn2_b64 vcc, exec, s[34:35]
	s_mov_b64 s[34:35], -1
	s_cbranch_vccnz .LBB0_484
	v_lshl_add_u64 v[14:15], v[150:151], 1, v[14:15]
	v_lshl_add_u64 v[16:17], v[14:15], 0, s[20:21]
	s_mov_b64 s[34:35], 0

.LBB0_486:
	v_mul_f32_e32 v12, v114, v199
	v_mul_f32_e32 v199, v118, v199
	v_fma_f32 v12, v118, v198, -v12
	v_fmac_f32_e32 v199, v114, v198
	v_mul_f32_e32 v198, v115, v201
	v_mul_f32_e32 v201, v119, v201
	v_fma_f32 v198, v119, v200, -v198
	v_fmac_f32_e32 v201, v115, v200
	v_mul_f32_e32 v200, v116, v195
	v_mul_f32_e32 v13, v120, v195
	v_fma_f32 v200, v120, v194, -v200
	v_fmac_f32_e32 v13, v116, v194
	v_mul_f32_e32 v194, v117, v197
	v_fma_f32 v195, v121, v196, -v194
	v_mul_f32_e32 v197, v121, v197
	v_fmac_f32_e32 v197, v117, v196
	v_cvt_pk_bf16_f32 v194, v12, v198
	v_cvt_pk_bf16_f32 v195, v200, v195
	v_cvt_pk_bf16_f32 v196, v199, v201
	v_cvt_pk_bf16_f32 v197, v13, v197
	s_nop 1
	v_permlane16_swap_b32 v194, v196
	v_permlane16_swap_b32 v195, v197
	v_lshl_add_u64 v[206:207], v[16:17], 0, v[204:205]
	global_store_dwordx4 v[206:207], v[194:197], off
	v_or_b32_e32 v12, s23, v173
	v_ashrrev_i32_e32 v13, 31, v12
	v_lshlrev_b64 v[14:15], 10, v[12:13]
	s_mov_b64 s[34:35], -1
	s_and_b64 vcc, exec, s[8:9]
	v_lshl_add_u64 v[14:15], s[12:13], 0, v[14:15]
	s_cbranch_vccnz .LBB0_490
	v_mov_b32_e32 v16, v10
	v_mov_b32_e32 v17, v151
	v_lshl_add_u64 v[16:17], v[16:17], 1, v[14:15]
	v_lshl_add_u64 v[16:17], v[16:17], 0, s[18:19]
	s_mov_b64 s[34:35], 0

.LBB0_492:
	s_waitcnt vmcnt(2)
	v_or_b32_e32 v202, s23, v174
	v_cmp_gt_i32_e32 vcc, s56, v202
	v_mov_b32_e32 v195, 0
	v_mov_b32_e32 v194, 1.0
	v_mov_b32_e32 v196, 1.0
	v_mov_b32_e32 v197, 0
	v_mov_b32_e32 v198, 1.0
	v_mov_b32_e32 v199, 0
	v_mov_b32_e32 v200, 1.0
	v_mov_b32_e32 v201, 0
	s_and_saveexec_b64 s[98:99], vcc
	s_cbranch_execz .Lrope_a_3
	s_bfe_u32 s25, s23, 0x50006
	v_mov_b32_e32 v194, s25
	v_cndmask_b32_e64 v194, v174, v194, s[4:5]
	v_lshlrev_b32_e32 v194, 8, v194
	v_mov_b32_e32 v195, v151
	v_lshl_add_u64 v[198:199], v[154:155], 0, v[194:195]
	global_load_dwordx4 v[194:197], v[198:199], off offset:16
	s_nop 0
	global_load_dwordx4 v[198:201], v[198:199], off
.Lrope_a_3:
	s_or_b64 exec, exec, s[98:99]
	v_mul_f32_e32 v114, v106, v7
	v_fma_f32 v114, v110, v6, -v114
	v_mul_f32_e32 v110, v110, v7
	v_fmac_f32_e32 v110, v106, v6
	v_mul_f32_e32 v106, v107, v9
	v_fma_f32 v106, v111, v8, -v106
	v_mul_f32_e32 v111, v111, v9
	v_fmac_f32_e32 v111, v107, v8
	v_mul_f32_e32 v107, v108, v3
	v_fma_f32 v107, v112, v2, -v107
	v_mul_f32_e32 v112, v112, v3
	v_fmac_f32_e32 v112, v108, v2
	v_mul_f32_e32 v108, v109, v5
	v_fma_f32 v108, v113, v4, -v108
	v_mul_f32_e32 v113, v113, v5
	v_cvt_pk_bf16_f32 v106, v114, v106
	v_cvt_pk_bf16_f32 v107, v107, v108
	s_and_b64 vcc, exec, s[10:11]
	s_mov_b64 s[34:35], -1
	v_fmac_f32_e32 v113, v109, v4
	v_cvt_pk_bf16_f32 v108, v110, v111
	v_cvt_pk_bf16_f32 v109, v112, v113
	s_nop 1
	v_permlane16_swap_b32 v106, v108
	v_permlane16_swap_b32 v107, v109
	v_lshl_add_u64 v[206:207], v[16:17], 0, v[204:205]
	global_store_dwordx4 v[206:207], v[106:109], off
	s_cbranch_vccnz .LBB0_494
	v_lshl_add_u64 v[14:15], v[150:151], 1, v[14:15]
	v_lshl_add_u64 v[16:17], v[14:15], 0, s[20:21]
	s_mov_b64 s[34:35], 0

.LBB0_496:
	v_mul_f32_e32 v12, v98, v7
	v_mul_f32_e32 v7, v102, v7
	v_fma_f32 v12, v102, v6, -v12
	v_fmac_f32_e32 v7, v98, v6
	v_mul_f32_e32 v6, v99, v9
	v_mul_f32_e32 v9, v103, v9
	v_fma_f32 v6, v103, v8, -v6
	v_fmac_f32_e32 v9, v99, v8
	v_mul_f32_e32 v8, v100, v3
	v_mul_f32_e32 v13, v104, v3
	v_fma_f32 v8, v104, v2, -v8
	v_fmac_f32_e32 v13, v100, v2
	v_mul_f32_e32 v2, v101, v5
	v_fma_f32 v3, v105, v4, -v2
	v_mul_f32_e32 v5, v105, v5
	v_fmac_f32_e32 v5, v101, v4
	v_cvt_pk_bf16_f32 v2, v12, v6
	v_cvt_pk_bf16_f32 v3, v8, v3
	v_cvt_pk_bf16_f32 v4, v7, v9
	v_cvt_pk_bf16_f32 v5, v13, v5
	s_nop 1
	v_permlane16_swap_b32 v2, v4
	v_permlane16_swap_b32 v3, v5
	v_lshl_add_u64 v[206:207], v[16:17], 0, v[204:205]
	global_store_dwordx4 v[206:207], v[2:5], off
	v_or_b32_e32 v12, s23, v174
	v_ashrrev_i32_e32 v13, 31, v12
	v_lshlrev_b64 v[14:15], 10, v[12:13]
	s_mov_b64 s[34:35], -1
	s_and_b64 vcc, exec, s[8:9]
	v_lshl_add_u64 v[14:15], s[12:13], 0, v[14:15]
	s_cbranch_vccnz .LBB0_500
	v_mov_b32_e32 v16, v10
	v_mov_b32_e32 v17, v151
	v_lshl_add_u64 v[16:17], v[16:17], 1, v[14:15]
	v_lshl_add_u64 v[16:17], v[16:17], 0, s[18:19]
	s_mov_b64 s[34:35], 0

.LBB0_502:
	s_waitcnt vmcnt(2)
	s_add_i32 s100, s23, 0x80
	v_or_b32_e32 v202, s100, v1
	v_cmp_gt_i32_e32 vcc, s56, v202
	v_mov_b32_e32 v3, 0
	v_mov_b32_e32 v2, 1.0
	v_mov_b32_e32 v4, 1.0
	v_mov_b32_e32 v5, 0
	v_mov_b32_e32 v6, 1.0
	v_mov_b32_e32 v7, 0
	v_mov_b32_e32 v8, 1.0
	v_mov_b32_e32 v9, 0
	s_and_saveexec_b64 s[98:99], vcc
	s_cbranch_execz .Lrope_a_4
	s_bfe_u32 s25, s100, 0x50006
	v_mov_b32_e32 v2, s25
	v_cndmask_b32_e64 v2, v1, v2, s[4:5]
	v_lshlrev_b32_e32 v2, 8, v2
	v_mov_b32_e32 v3, v151
	v_lshl_add_u64 v[6:7], v[154:155], 0, v[2:3]
	global_load_dwordx4 v[2:5], v[6:7], off offset:16
	s_nop 0
	global_load_dwordx4 v[6:9], v[6:7], off
.Lrope_a_4:
	s_or_b64 exec, exec, s[98:99]
	v_mul_f32_e32 v98, v90, v199
	v_fma_f32 v98, v94, v198, -v98
	v_mul_f32_e32 v94, v94, v199
	v_fmac_f32_e32 v94, v90, v198
	v_mul_f32_e32 v90, v91, v201
	v_fma_f32 v90, v95, v200, -v90
	v_mul_f32_e32 v95, v95, v201
	v_fmac_f32_e32 v95, v91, v200
	v_mul_f32_e32 v91, v92, v195
	v_fma_f32 v91, v96, v194, -v91
	v_mul_f32_e32 v96, v96, v195
	v_fmac_f32_e32 v96, v92, v194
	v_mul_f32_e32 v92, v93, v197
	v_fma_f32 v92, v97, v196, -v92
	v_mul_f32_e32 v97, v97, v197
	v_cvt_pk_bf16_f32 v90, v98, v90
	v_cvt_pk_bf16_f32 v91, v91, v92
	s_and_b64 vcc, exec, s[10:11]
	s_mov_b64 s[34:35], -1
	v_fmac_f32_e32 v97, v93, v196
	v_cvt_pk_bf16_f32 v92, v94, v95
	v_cvt_pk_bf16_f32 v93, v96, v97
	s_nop 1
	v_permlane16_swap_b32 v90, v92
	v_permlane16_swap_b32 v91, v93
	v_lshl_add_u64 v[206:207], v[16:17], 0, v[204:205]
	global_store_dwordx4 v[206:207], v[90:93], off
	s_cbranch_vccnz .LBB0_504
	v_lshl_add_u64 v[14:15], v[150:151], 1, v[14:15]
	v_lshl_add_u64 v[16:17], v[14:15], 0, s[20:21]
	s_mov_b64 s[34:35], 0

.LBB0_506:
	v_mul_f32_e32 v12, v82, v199
	v_mul_f32_e32 v199, v86, v199
	v_fma_f32 v12, v86, v198, -v12
	v_fmac_f32_e32 v199, v82, v198
	v_mul_f32_e32 v198, v83, v201
	v_mul_f32_e32 v201, v87, v201
	v_fma_f32 v198, v87, v200, -v198
	v_fmac_f32_e32 v201, v83, v200
	v_mul_f32_e32 v200, v84, v195
	v_mul_f32_e32 v13, v88, v195
	v_fma_f32 v200, v88, v194, -v200
	v_fmac_f32_e32 v13, v84, v194
	v_mul_f32_e32 v194, v85, v197
	v_fma_f32 v195, v89, v196, -v194
	v_mul_f32_e32 v197, v89, v197
	v_fmac_f32_e32 v197, v85, v196
	v_cvt_pk_bf16_f32 v194, v12, v198
	v_cvt_pk_bf16_f32 v195, v200, v195
	v_cvt_pk_bf16_f32 v196, v199, v201
	v_cvt_pk_bf16_f32 v197, v13, v197
	s_nop 1
	v_permlane16_swap_b32 v194, v196
	v_permlane16_swap_b32 v195, v197
	v_lshl_add_u64 v[206:207], v[16:17], 0, v[204:205]
	global_store_dwordx4 v[206:207], v[194:197], off
	s_addk_i32 s23, 0x80
	v_or_b32_e32 v12, s23, v1
	v_ashrrev_i32_e32 v13, 31, v12
	v_lshlrev_b64 v[14:15], 10, v[12:13]
	s_mov_b64 s[34:35], -1
	s_and_b64 vcc, exec, s[8:9]
	v_lshl_add_u64 v[14:15], s[12:13], 0, v[14:15]
	s_cbranch_vccnz .LBB0_510
	v_mov_b32_e32 v16, v10
	v_mov_b32_e32 v17, v151
	v_lshl_add_u64 v[16:17], v[16:17], 1, v[14:15]
	v_lshl_add_u64 v[16:17], v[16:17], 0, s[18:19]
	s_mov_b64 s[34:35], 0

.LBB0_512:
	s_waitcnt vmcnt(2)
	v_or_b32_e32 v202, s23, v172
	v_cmp_gt_i32_e32 vcc, s56, v202
	v_mov_b32_e32 v195, 0
	v_mov_b32_e32 v194, 1.0
	v_mov_b32_e32 v196, 1.0
	v_mov_b32_e32 v197, 0
	v_mov_b32_e32 v198, 1.0
	v_mov_b32_e32 v199, 0
	v_mov_b32_e32 v200, 1.0
	v_mov_b32_e32 v201, 0
	s_and_saveexec_b64 s[98:99], vcc
	s_cbranch_execz .Lrope_a_5
	s_bfe_u32 s25, s23, 0x50006
	v_mov_b32_e32 v194, s25
	v_cndmask_b32_e64 v194, v172, v194, s[4:5]
	v_lshlrev_b32_e32 v194, 8, v194
	v_mov_b32_e32 v195, v151
	v_lshl_add_u64 v[198:199], v[154:155], 0, v[194:195]
	global_load_dwordx4 v[194:197], v[198:199], off offset:16
	s_nop 0
	global_load_dwordx4 v[198:201], v[198:199], off
.Lrope_a_5:
	s_or_b64 exec, exec, s[98:99]
	v_mul_f32_e32 v82, v74, v7
	v_fma_f32 v82, v78, v6, -v82
	v_mul_f32_e32 v78, v78, v7
	v_fmac_f32_e32 v78, v74, v6
	v_mul_f32_e32 v74, v75, v9
	v_fma_f32 v74, v79, v8, -v74
	v_mul_f32_e32 v79, v79, v9
	v_fmac_f32_e32 v79, v75, v8
	v_mul_f32_e32 v75, v76, v3
	v_fma_f32 v75, v80, v2, -v75
	v_mul_f32_e32 v80, v80, v3
	v_fmac_f32_e32 v80, v76, v2
	v_mul_f32_e32 v76, v77, v5
	v_fma_f32 v76, v81, v4, -v76
	v_mul_f32_e32 v81, v81, v5
	v_cvt_pk_bf16_f32 v74, v82, v74
	v_cvt_pk_bf16_f32 v75, v75, v76
	s_and_b64 vcc, exec, s[10:11]
	s_mov_b64 s[34:35], -1
	v_fmac_f32_e32 v81, v77, v4
	v_cvt_pk_bf16_f32 v76, v78, v79
	v_cvt_pk_bf16_f32 v77, v80, v81
	s_nop 1
	v_permlane16_swap_b32 v74, v76
	v_permlane16_swap_b32 v75, v77
	v_lshl_add_u64 v[206:207], v[16:17], 0, v[204:205]
	global_store_dwordx4 v[206:207], v[74:77], off
	s_cbranch_vccnz .LBB0_514
	v_lshl_add_u64 v[14:15], v[150:151], 1, v[14:15]
	v_lshl_add_u64 v[16:17], v[14:15], 0, s[20:21]
	s_mov_b64 s[34:35], 0

.LBB0_516:
	v_mul_f32_e32 v12, v66, v7
	v_mul_f32_e32 v7, v70, v7
	v_fma_f32 v12, v70, v6, -v12
	v_fmac_f32_e32 v7, v66, v6
	v_mul_f32_e32 v6, v67, v9
	v_mul_f32_e32 v9, v71, v9
	v_fma_f32 v6, v71, v8, -v6
	v_fmac_f32_e32 v9, v67, v8
	v_mul_f32_e32 v8, v68, v3
	v_mul_f32_e32 v13, v72, v3
	v_fma_f32 v8, v72, v2, -v8
	v_fmac_f32_e32 v13, v68, v2
	v_mul_f32_e32 v2, v69, v5
	v_fma_f32 v3, v73, v4, -v2
	v_mul_f32_e32 v5, v73, v5
	v_fmac_f32_e32 v5, v69, v4
	v_cvt_pk_bf16_f32 v2, v12, v6
	v_cvt_pk_bf16_f32 v3, v8, v3
	v_cvt_pk_bf16_f32 v4, v7, v9
	v_cvt_pk_bf16_f32 v5, v13, v5
	s_nop 1
	v_permlane16_swap_b32 v2, v4
	v_permlane16_swap_b32 v3, v5
	v_lshl_add_u64 v[206:207], v[16:17], 0, v[204:205]
	global_store_dwordx4 v[206:207], v[2:5], off
	v_or_b32_e32 v12, s23, v172
	v_ashrrev_i32_e32 v13, 31, v12
	v_lshlrev_b64 v[14:15], 10, v[12:13]
	s_mov_b64 s[34:35], -1
	s_and_b64 vcc, exec, s[8:9]
	v_lshl_add_u64 v[14:15], s[12:13], 0, v[14:15]
	s_cbranch_vccnz .LBB0_520
	v_mov_b32_e32 v16, v10
	v_mov_b32_e32 v17, v151
	v_lshl_add_u64 v[16:17], v[16:17], 1, v[14:15]
	v_lshl_add_u64 v[16:17], v[16:17], 0, s[18:19]
	s_mov_b64 s[34:35], 0

.Lrope_a_6:
	s_or_b64 exec, exec, s[98:99]
	v_mul_f32_e32 v66, v58, v199
	v_fma_f32 v66, v62, v198, -v66
	v_mul_f32_e32 v62, v62, v199
	v_fmac_f32_e32 v62, v58, v198
	v_mul_f32_e32 v58, v59, v201
	v_fma_f32 v58, v63, v200, -v58
	v_mul_f32_e32 v63, v63, v201
	v_fmac_f32_e32 v63, v59, v200
	v_mul_f32_e32 v59, v60, v195
	v_fma_f32 v59, v64, v194, -v59
	v_mul_f32_e32 v64, v64, v195
	v_fmac_f32_e32 v64, v60, v194
	v_mul_f32_e32 v60, v61, v197
	v_fma_f32 v60, v65, v196, -v60
	v_mul_f32_e32 v65, v65, v197
	v_cvt_pk_bf16_f32 v58, v66, v58
	v_cvt_pk_bf16_f32 v59, v59, v60
	s_and_b64 vcc, exec, s[10:11]
	s_mov_b64 s[34:35], -1
	v_fmac_f32_e32 v65, v61, v196
	v_cvt_pk_bf16_f32 v60, v62, v63
	v_cvt_pk_bf16_f32 v61, v64, v65
	s_nop 1
	v_permlane16_swap_b32 v58, v60
	v_permlane16_swap_b32 v59, v61
	v_lshl_add_u64 v[206:207], v[16:17], 0, v[204:205]
	global_store_dwordx4 v[206:207], v[58:61], off
	s_cbranch_vccnz .LBB0_524
	v_lshl_add_u64 v[14:15], v[150:151], 1, v[14:15]
	v_lshl_add_u64 v[16:17], v[14:15], 0, s[20:21]
	s_mov_b64 s[34:35], 0

.LBB0_526:
	v_mul_f32_e32 v12, v50, v199
	v_mul_f32_e32 v199, v54, v199
	v_fma_f32 v12, v54, v198, -v12
	v_fmac_f32_e32 v199, v50, v198
	v_mul_f32_e32 v198, v51, v201
	v_mul_f32_e32 v201, v55, v201
	v_fma_f32 v198, v55, v200, -v198
	v_fmac_f32_e32 v201, v51, v200
	v_mul_f32_e32 v200, v52, v195
	v_mul_f32_e32 v13, v56, v195
	v_fma_f32 v200, v56, v194, -v200
	v_fmac_f32_e32 v13, v52, v194
	v_mul_f32_e32 v194, v53, v197
	v_fma_f32 v195, v57, v196, -v194
	v_mul_f32_e32 v197, v57, v197
	v_fmac_f32_e32 v197, v53, v196
	v_cvt_pk_bf16_f32 v194, v12, v198
	v_cvt_pk_bf16_f32 v195, v200, v195
	v_cvt_pk_bf16_f32 v196, v199, v201
	v_cvt_pk_bf16_f32 v197, v13, v197
	s_nop 1
	v_permlane16_swap_b32 v194, v196
	v_permlane16_swap_b32 v195, v197
	v_lshl_add_u64 v[206:207], v[16:17], 0, v[204:205]
	global_store_dwordx4 v[206:207], v[194:197], off
	v_or_b32_e32 v12, s23, v173
	v_ashrrev_i32_e32 v13, 31, v12
	v_lshlrev_b64 v[14:15], 10, v[12:13]
	s_mov_b64 s[34:35], -1
	s_and_b64 vcc, exec, s[8:9]
	v_lshl_add_u64 v[14:15], s[12:13], 0, v[14:15]
	s_cbranch_vccnz .LBB0_530
	v_mov_b32_e32 v16, v10
	v_mov_b32_e32 v17, v151
	v_lshl_add_u64 v[16:17], v[16:17], 1, v[14:15]
	v_lshl_add_u64 v[16:17], v[16:17], 0, s[18:19]
	s_mov_b64 s[34:35], 0

.LBB0_532:
	s_waitcnt vmcnt(2)
	v_mul_f32_e32 v50, v42, v7
	v_fma_f32 v50, v46, v6, -v50
	v_mul_f32_e32 v46, v46, v7
	v_fmac_f32_e32 v46, v42, v6
	v_mul_f32_e32 v42, v43, v9
	v_fma_f32 v42, v47, v8, -v42
	v_mul_f32_e32 v47, v47, v9
	v_fmac_f32_e32 v47, v43, v8
	v_mul_f32_e32 v43, v44, v3
	v_fma_f32 v43, v48, v2, -v43
	v_mul_f32_e32 v48, v48, v3
	v_fmac_f32_e32 v48, v44, v2
	v_mul_f32_e32 v44, v45, v5
	v_fma_f32 v44, v49, v4, -v44
	v_mul_f32_e32 v49, v49, v5
	v_cvt_pk_bf16_f32 v42, v50, v42
	v_cvt_pk_bf16_f32 v43, v43, v44
	s_and_b64 vcc, exec, s[10:11]
	s_mov_b64 s[34:35], -1
	v_fmac_f32_e32 v49, v45, v4
	v_cvt_pk_bf16_f32 v44, v46, v47
	v_cvt_pk_bf16_f32 v45, v48, v49
	s_nop 1
	v_permlane16_swap_b32 v42, v44
	v_permlane16_swap_b32 v43, v45
	v_lshl_add_u64 v[206:207], v[16:17], 0, v[204:205]
	global_store_dwordx4 v[206:207], v[42:45], off
	s_cbranch_vccnz .LBB0_534
	v_lshl_add_u64 v[14:15], v[150:151], 1, v[14:15]
	v_lshl_add_u64 v[16:17], v[14:15], 0, s[20:21]
	s_mov_b64 s[34:35], 0

.LBB0_536:
	v_mul_f32_e32 v12, v34, v7
	v_mul_f32_e32 v7, v38, v7
	v_fma_f32 v12, v38, v6, -v12
	v_fmac_f32_e32 v7, v34, v6
	v_mul_f32_e32 v6, v35, v9
	v_mul_f32_e32 v9, v39, v9
	v_fma_f32 v6, v39, v8, -v6
	v_fmac_f32_e32 v9, v35, v8
	v_mul_f32_e32 v8, v36, v3
	v_mul_f32_e32 v13, v40, v3
	v_fma_f32 v8, v40, v2, -v8
	v_fmac_f32_e32 v13, v36, v2
	v_mul_f32_e32 v2, v37, v5
	v_fma_f32 v3, v41, v4, -v2
	v_mul_f32_e32 v5, v41, v5
	v_fmac_f32_e32 v5, v37, v4
	v_cvt_pk_bf16_f32 v2, v12, v6
	v_cvt_pk_bf16_f32 v3, v8, v3
	v_cvt_pk_bf16_f32 v4, v7, v9
	v_cvt_pk_bf16_f32 v5, v13, v5
	s_nop 1
	v_permlane16_swap_b32 v2, v4
	v_permlane16_swap_b32 v3, v5
	v_lshl_add_u64 v[206:207], v[16:17], 0, v[204:205]
	global_store_dwordx4 v[206:207], v[2:5], off
	v_or_b32_e32 v12, s23, v174
	v_cmp_gt_i32_e32 vcc, s56, v12
	v_mov_b32_e32 v7, 0
	v_mov_b32_e32 v6, 1.0
	v_mov_b32_e32 v8, 1.0
	v_mov_b32_e32 v9, 0
	v_mov_b32_e32 v2, 1.0
	v_mov_b32_e32 v3, 0
	v_mov_b32_e32 v4, 1.0
	v_mov_b32_e32 v5, 0
	s_and_saveexec_b64 s[34:35], vcc
	s_cbranch_execz .LBB0_538
	s_bfe_u32 s23, s23, 0x50006
	v_mov_b32_e32 v2, s23
	v_cndmask_b32_e64 v2, v174, v2, s[4:5]
	v_lshlrev_b32_e32 v2, 8, v2
	v_mov_b32_e32 v3, v151
	v_lshl_add_u64 v[2:3], v[154:155], 0, v[2:3]
	global_load_dwordx4 v[6:9], v[2:3], off offset:16
	s_nop 0
	global_load_dwordx4 v[2:5], v[2:3], off

.LBB0_2364:
	v_mov_b32_e32 v12, v21
	v_mov_b32_e32 v13, v25
	v_pk_mul_f32 v[12:13], v[12:13], v[8:9]
	s_and_b64 vcc, exec, s[8:9]
	v_add_f32_e32 v14, v12, v13
	v_mov_b32_e32 v12, v25
	v_mov_b32_e32 v13, v21
	v_pk_mul_f32 v[8:9], v[12:13], v[8:9]
	v_mov_b32_e32 v21, v24
	v_mov_b32_e32 v25, v20
	v_sub_f32_e32 v12, v8, v9
	v_pk_mul_f32 v[8:9], v[20:21], v[6:7]
	v_pk_mul_f32 v[6:7], v[24:25], v[6:7]
	v_add_f32_e32 v8, v8, v9
	v_sub_f32_e32 v9, v6, v7
	v_mov_b32_e32 v6, v19
	v_mov_b32_e32 v7, v23
	v_pk_mul_f32 v[6:7], v[6:7], v[4:5]
	s_mov_b32 s10, s24
	v_add_f32_e32 v13, v6, v7
	v_mov_b32_e32 v6, v23
	v_mov_b32_e32 v7, v19
	v_pk_mul_f32 v[4:5], v[6:7], v[4:5]
	v_mov_b32_e32 v19, v22
	v_mov_b32_e32 v23, v18
	v_sub_f32_e32 v6, v4, v5
	v_pk_mul_f32 v[4:5], v[18:19], v[2:3]
	v_pk_mul_f32 v[2:3], v[22:23], v[2:3]
	v_add_f32_e32 v4, v4, v5
	v_sub_f32_e32 v2, v2, v3
	v_cvt_pk_bf16_f32 v2, v2, v6
	v_cvt_pk_bf16_f32 v3, v9, v12
	v_cvt_pk_bf16_f32 v4, v4, v13
	v_cvt_pk_bf16_f32 v5, v8, v14
	s_nop 1
	v_permlane16_swap_b32 v2, v4
	v_permlane16_swap_b32 v3, v5
	v_lshl_add_u64 v[206:207], v[10:11], 0, v[204:205]
	global_store_dwordx4 v[206:207], v[2:5], off
	s_mov_b32 s12, s26
	s_mov_b64 s[36:37], s[30:31]
	s_mov_b64 s[34:35], s[28:29]
	s_cbranch_vccnz .LBB0_2449

.LBB0_2368:
	ds_read_b128 v[2:5], v176
	ds_read_b128 v[6:9], v177
	ds_read_b128 v[10:13], v178
	ds_read_b128 v[14:17], v179
	s_add_u32 s36, s34, 0xfffc0080
	s_addc_u32 s37, s35, -1
	s_cmp_eq_u32 s71, 12
	s_cselect_b32 s39, s11, s37
	s_cselect_b32 s38, s13, s36
	s_cselect_b32 s37, s25, s70
	s_cselect_b32 s36, s27, s69
	v_lshl_add_u64 v[164:165], s[34:35], 0, v[156:157]
	s_add_i32 m0, s47, 0xc000
	ds_read_b128 v[194:197], v192
	ds_read_b128 v[198:201], v192 offset:1024
	ds_read_b128 v[216:219], v192 offset:2048
	ds_read_b128 v[220:223], v192 offset:3072
	ds_read_b128 v[224:227], v192 offset:4096
	ds_read_b128 v[228:231], v192 offset:5120
	ds_read_b128 v[232:235], v192 offset:6144
	ds_read_b128 v[236:239], v192 offset:7168
	global_load_lds_dwordx4 v[164:165], off
	v_lshl_add_u64 v[164:165], s[34:35], 0, v[158:159]
	s_add_i32 m0, s47, 0xe000
	s_nop 0
	global_load_lds_dwordx4 v[164:165], off
	s_waitcnt lgkmcnt(8)
	s_barrier
	s_waitcnt lgkmcnt(0)
	s_setprio 1
	s_waitcnt lgkmcnt(0)
	v_mfma_scale_f32_16x16x128_f8f6f4 v[142:145], v[2:9], v[194:201], v[142:145], v193, v193 op_sel_hi:[0,0,0]
	v_mfma_scale_f32_16x16x128_f8f6f4 v[138:141], v[10:17], v[194:201], v[138:141], v193, v193 op_sel_hi:[0,0,0]
	v_mfma_scale_f32_16x16x128_f8f6f4 v[126:129], v[2:9], v[216:223], v[126:129], v193, v193 op_sel_hi:[0,0,0]
	v_mfma_scale_f32_16x16x128_f8f6f4 v[122:125], v[10:17], v[216:223], v[122:125], v193, v193 op_sel_hi:[0,0,0]
	v_mfma_scale_f32_16x16x128_f8f6f4 v[110:113], v[2:9], v[224:231], v[110:113], v193, v193 op_sel_hi:[0,0,0]
	v_mfma_scale_f32_16x16x128_f8f6f4 v[106:109], v[10:17], v[224:231], v[106:109], v193, v193 op_sel_hi:[0,0,0]
	v_mfma_scale_f32_16x16x128_f8f6f4 v[94:97], v[2:9], v[232:239], v[94:97], v193, v193 op_sel_hi:[0,0,0]
	v_mfma_scale_f32_16x16x128_f8f6f4 v[90:93], v[10:17], v[232:239], v[90:93], v193, v193 op_sel_hi:[0,0,0]
	s_setprio 0
	s_barrier
	s_mov_b32 m0, s52
	v_lshl_add_u64 v[164:165], s[36:37], 0, v[146:147]
	ds_read_b128 v[240:243], v180
	ds_read_b128 v[244:247], v181
	ds_read_b128 v[202:205], v182
	ds_read_b128 v[206:209], v183
	global_load_lds_dwordx4 v[164:165], off
	v_lshl_add_u64 v[166:167], s[36:37], 0, v[148:149]
	s_mov_b32 m0, s53
	s_nop 0
	global_load_lds_dwordx4 v[166:167], off
	s_barrier
	s_waitcnt lgkmcnt(0)
	s_setprio 1
	s_waitcnt lgkmcnt(0)
	v_mfma_scale_f32_16x16x128_f8f6f4 v[134:137], v[240:247], v[194:201], v[134:137], v193, v193 op_sel_hi:[0,0,0]
	v_mfma_scale_f32_16x16x128_f8f6f4 v[130:133], v[202:209], v[194:201], v[130:133], v193, v193 op_sel_hi:[0,0,0]
	v_mfma_scale_f32_16x16x128_f8f6f4 v[118:121], v[240:247], v[216:223], v[118:121], v193, v193 op_sel_hi:[0,0,0]
	v_mfma_scale_f32_16x16x128_f8f6f4 v[114:117], v[202:209], v[216:223], v[114:117], v193, v193 op_sel_hi:[0,0,0]
	v_mfma_scale_f32_16x16x128_f8f6f4 v[102:105], v[240:247], v[224:231], v[102:105], v193, v193 op_sel_hi:[0,0,0]
	v_mfma_scale_f32_16x16x128_f8f6f4 v[98:101], v[202:209], v[224:231], v[98:101], v193, v193 op_sel_hi:[0,0,0]
	v_mfma_scale_f32_16x16x128_f8f6f4 v[86:89], v[240:247], v[232:239], v[86:89], v193, v193 op_sel_hi:[0,0,0]
	v_mfma_scale_f32_16x16x128_f8f6f4 v[82:85], v[202:209], v[232:239], v[82:85], v193, v193 op_sel_hi:[0,0,0]
	s_setprio 0
	s_mov_b32 m0, s47
	v_lshl_add_u64 v[168:169], s[38:39], 0, v[146:147]
	s_barrier
	ds_read_b128 v[194:197], v192 offset:16384
	ds_read_b128 v[198:201], v192 offset:17408
	ds_read_b128 v[216:219], v192 offset:18432
	ds_read_b128 v[220:223], v192 offset:19456
	ds_read_b128 v[224:227], v192 offset:20480
	ds_read_b128 v[228:231], v192 offset:21504
	ds_read_b128 v[232:235], v192 offset:22528
	ds_read_b128 v[236:239], v192 offset:23552
	global_load_lds_dwordx4 v[168:169], off
	v_lshl_add_u64 v[170:171], s[38:39], 0, v[148:149]
	s_mov_b32 m0, s54
	s_nop 0
	global_load_lds_dwordx4 v[170:171], off
	s_barrier
	s_waitcnt lgkmcnt(0)
	s_setprio 1
	s_waitcnt lgkmcnt(0)
	v_mfma_scale_f32_16x16x128_f8f6f4 v[78:81], v[2:9], v[194:201], v[78:81], v193, v193 op_sel_hi:[0,0,0]
	v_mfma_scale_f32_16x16x128_f8f6f4 v[74:77], v[10:17], v[194:201], v[74:77], v193, v193 op_sel_hi:[0,0,0]
	v_mfma_scale_f32_16x16x128_f8f6f4 v[62:65], v[2:9], v[216:223], v[62:65], v193, v193 op_sel_hi:[0,0,0]
	v_mfma_scale_f32_16x16x128_f8f6f4 v[58:61], v[10:17], v[216:223], v[58:61], v193, v193 op_sel_hi:[0,0,0]
	v_mfma_scale_f32_16x16x128_f8f6f4 v[46:49], v[2:9], v[224:231], v[46:49], v193, v193 op_sel_hi:[0,0,0]
	v_mfma_scale_f32_16x16x128_f8f6f4 v[42:45], v[10:17], v[224:231], v[42:45], v193, v193 op_sel_hi:[0,0,0]
	v_mfma_scale_f32_16x16x128_f8f6f4 v[30:33], v[2:9], v[232:239], v[30:33], v193, v193 op_sel_hi:[0,0,0]
	v_mfma_scale_f32_16x16x128_f8f6f4 v[26:29], v[10:17], v[232:239], v[26:29], v193, v193 op_sel_hi:[0,0,0]
	s_setprio 0
	s_barrier
	s_add_u32 s78, s36, 0x40000
	s_addc_u32 s79, s37, 0
	s_mov_b32 m0, s55
	v_lshl_add_u64 v[2:3], s[78:79], 0, v[146:147]
	global_load_lds_dwordx4 v[2:3], off
	v_lshl_add_u64 v[2:3], s[78:79], 0, v[148:149]
	s_mov_b32 m0, s56
	s_nop 0
	global_load_lds_dwordx4 v[2:3], off
	s_waitcnt vmcnt(6)
	s_barrier
	s_setprio 1
	v_mfma_scale_f32_16x16x128_f8f6f4 v[70:73], v[240:247], v[194:201], v[70:73], v193, v193 op_sel_hi:[0,0,0]
	v_mfma_scale_f32_16x16x128_f8f6f4 v[66:69], v[202:209], v[194:201], v[66:69], v193, v193 op_sel_hi:[0,0,0]
	v_mfma_scale_f32_16x16x128_f8f6f4 v[54:57], v[240:247], v[216:223], v[54:57], v193, v193 op_sel_hi:[0,0,0]
	v_mfma_scale_f32_16x16x128_f8f6f4 v[50:53], v[202:209], v[216:223], v[50:53], v193, v193 op_sel_hi:[0,0,0]
	v_mfma_scale_f32_16x16x128_f8f6f4 v[38:41], v[240:247], v[224:231], v[38:41], v193, v193 op_sel_hi:[0,0,0]
	v_mfma_scale_f32_16x16x128_f8f6f4 v[34:37], v[202:209], v[224:231], v[34:37], v193, v193 op_sel_hi:[0,0,0]
	v_mfma_scale_f32_16x16x128_f8f6f4 v[22:25], v[240:247], v[232:239], v[22:25], v193, v193 op_sel_hi:[0,0,0]
	v_mfma_scale_f32_16x16x128_f8f6f4 v[18:21], v[202:209], v[232:239], v[18:21], v193, v193 op_sel_hi:[0,0,0]
	s_setprio 0
	s_barrier
	ds_read_b128 v[2:5], v184
	ds_read_b128 v[6:9], v185
	ds_read_b128 v[10:13], v186
	ds_read_b128 v[14:17], v187
	s_add_u32 s38, s38, 0x40000
	s_addc_u32 s39, s39, 0
	s_mov_b32 m0, s57
	v_lshl_add_u64 v[232:233], s[38:39], 0, v[146:147]
	ds_read_b128 v[194:197], v192 offset:32768
	ds_read_b128 v[198:201], v192 offset:33792
	ds_read_b128 v[202:205], v192 offset:34816
	ds_read_b128 v[206:209], v192 offset:35840
	ds_read_b128 v[216:219], v192 offset:36864
	ds_read_b128 v[220:223], v192 offset:37888
	ds_read_b128 v[224:227], v192 offset:38912
	ds_read_b128 v[228:231], v192 offset:39936
	global_load_lds_dwordx4 v[232:233], off
	v_lshl_add_u64 v[232:233], s[38:39], 0, v[148:149]
	s_mov_b32 m0, s58
	s_nop 0
	global_load_lds_dwordx4 v[232:233], off
	s_waitcnt lgkmcnt(8)
	s_barrier
	s_waitcnt lgkmcnt(0)
	s_setprio 1
	s_waitcnt lgkmcnt(0)
	v_mfma_scale_f32_16x16x128_f8f6f4 v[142:145], v[2:9], v[194:201], v[142:145], v193, v193 op_sel_hi:[0,0,0]
	v_mfma_scale_f32_16x16x128_f8f6f4 v[138:141], v[10:17], v[194:201], v[138:141], v193, v193 op_sel_hi:[0,0,0]
	v_mfma_scale_f32_16x16x128_f8f6f4 v[126:129], v[2:9], v[202:209], v[126:129], v193, v193 op_sel_hi:[0,0,0]
	v_mfma_scale_f32_16x16x128_f8f6f4 v[122:125], v[10:17], v[202:209], v[122:125], v193, v193 op_sel_hi:[0,0,0]
	v_mfma_scale_f32_16x16x128_f8f6f4 v[110:113], v[2:9], v[216:223], v[110:113], v193, v193 op_sel_hi:[0,0,0]
	v_mfma_scale_f32_16x16x128_f8f6f4 v[106:109], v[10:17], v[216:223], v[106:109], v193, v193 op_sel_hi:[0,0,0]
	v_mfma_scale_f32_16x16x128_f8f6f4 v[94:97], v[2:9], v[224:231], v[94:97], v193, v193 op_sel_hi:[0,0,0]
	v_mfma_scale_f32_16x16x128_f8f6f4 v[90:93], v[10:17], v[224:231], v[90:93], v193, v193 op_sel_hi:[0,0,0]
	s_setprio 0
	s_barrier
	s_mov_b32 m0, s62
	v_lshl_add_u64 v[164:165], v[164:165], 0, s[16:17]
	ds_read_b128 v[232:235], v188
	ds_read_b128 v[236:239], v189
	ds_read_b128 v[240:243], v190
	ds_read_b128 v[244:247], v191
	global_load_lds_dwordx4 v[164:165], off
	v_lshl_add_u64 v[164:165], v[166:167], 0, s[16:17]
	s_mov_b32 m0, s63
	s_nop 0
	global_load_lds_dwordx4 v[164:165], off
	s_barrier
	s_waitcnt lgkmcnt(0)
	s_setprio 1
	s_waitcnt lgkmcnt(0)
	v_mfma_scale_f32_16x16x128_f8f6f4 v[134:137], v[232:239], v[194:201], v[134:137], v193, v193 op_sel_hi:[0,0,0]
	v_mfma_scale_f32_16x16x128_f8f6f4 v[130:133], v[240:247], v[194:201], v[130:133], v193, v193 op_sel_hi:[0,0,0]
	v_mfma_scale_f32_16x16x128_f8f6f4 v[118:121], v[232:239], v[202:209], v[118:121], v193, v193 op_sel_hi:[0,0,0]
	v_mfma_scale_f32_16x16x128_f8f6f4 v[114:117], v[240:247], v[202:209], v[114:117], v193, v193 op_sel_hi:[0,0,0]
	v_mfma_scale_f32_16x16x128_f8f6f4 v[102:105], v[232:239], v[216:223], v[102:105], v193, v193 op_sel_hi:[0,0,0]
	v_mfma_scale_f32_16x16x128_f8f6f4 v[98:101], v[240:247], v[216:223], v[98:101], v193, v193 op_sel_hi:[0,0,0]
	v_mfma_scale_f32_16x16x128_f8f6f4 v[86:89], v[232:239], v[224:231], v[86:89], v193, v193 op_sel_hi:[0,0,0]
	v_mfma_scale_f32_16x16x128_f8f6f4 v[82:85], v[240:247], v[224:231], v[82:85], v193, v193 op_sel_hi:[0,0,0]
	s_setprio 0
	s_mov_b32 m0, s64
	v_lshl_add_u64 v[164:165], v[168:169], 0, s[16:17]
	s_barrier
	ds_read_b128 v[194:197], v192 offset:49152
	ds_read_b128 v[198:201], v192 offset:50176
	ds_read_b128 v[202:205], v192 offset:51200
	ds_read_b128 v[206:209], v192 offset:52224
	ds_read_b128 v[216:219], v192 offset:53248
	ds_read_b128 v[220:223], v192 offset:54272
	ds_read_b128 v[224:227], v192 offset:55296
	ds_read_b128 v[228:231], v192 offset:56320
	global_load_lds_dwordx4 v[164:165], off
	v_lshl_add_u64 v[164:165], v[170:171], 0, s[16:17]
	s_mov_b32 m0, s65
	s_nop 0
	global_load_lds_dwordx4 v[164:165], off
	s_barrier
	s_waitcnt lgkmcnt(0)
	s_setprio 1
	s_waitcnt lgkmcnt(0)
	v_mfma_scale_f32_16x16x128_f8f6f4 v[78:81], v[2:9], v[194:201], v[78:81], v193, v193 op_sel_hi:[0,0,0]
	v_mfma_scale_f32_16x16x128_f8f6f4 v[74:77], v[10:17], v[194:201], v[74:77], v193, v193 op_sel_hi:[0,0,0]
	v_mfma_scale_f32_16x16x128_f8f6f4 v[62:65], v[2:9], v[202:209], v[62:65], v193, v193 op_sel_hi:[0,0,0]
	v_mfma_scale_f32_16x16x128_f8f6f4 v[58:61], v[10:17], v[202:209], v[58:61], v193, v193 op_sel_hi:[0,0,0]
	v_mfma_scale_f32_16x16x128_f8f6f4 v[46:49], v[2:9], v[216:223], v[46:49], v193, v193 op_sel_hi:[0,0,0]
	v_mfma_scale_f32_16x16x128_f8f6f4 v[42:45], v[10:17], v[216:223], v[42:45], v193, v193 op_sel_hi:[0,0,0]
	v_mfma_scale_f32_16x16x128_f8f6f4 v[30:33], v[2:9], v[224:231], v[30:33], v193, v193 op_sel_hi:[0,0,0]
	v_mfma_scale_f32_16x16x128_f8f6f4 v[26:29], v[10:17], v[224:231], v[26:29], v193, v193 op_sel_hi:[0,0,0]
	s_setprio 0
	s_barrier
	s_add_u32 s36, s36, 0x40080
	s_addc_u32 s37, s37, 0
	s_mov_b32 m0, s66
	v_lshl_add_u64 v[2:3], s[36:37], 0, v[146:147]
	global_load_lds_dwordx4 v[2:3], off
	v_lshl_add_u64 v[2:3], s[36:37], 0, v[148:149]
	s_mov_b32 m0, s67
	s_nop 0
	global_load_lds_dwordx4 v[2:3], off
	s_waitcnt vmcnt(6)
	s_barrier
	s_setprio 1
	v_mfma_scale_f32_16x16x128_f8f6f4 v[70:73], v[232:239], v[194:201], v[70:73], v193, v193 op_sel_hi:[0,0,0]
	v_mfma_scale_f32_16x16x128_f8f6f4 v[66:69], v[240:247], v[194:201], v[66:69], v193, v193 op_sel_hi:[0,0,0]
	v_mfma_scale_f32_16x16x128_f8f6f4 v[54:57], v[232:239], v[202:209], v[54:57], v193, v193 op_sel_hi:[0,0,0]
	v_mfma_scale_f32_16x16x128_f8f6f4 v[50:53], v[240:247], v[202:209], v[50:53], v193, v193 op_sel_hi:[0,0,0]
	v_mfma_scale_f32_16x16x128_f8f6f4 v[38:41], v[232:239], v[216:223], v[38:41], v193, v193 op_sel_hi:[0,0,0]
	v_mfma_scale_f32_16x16x128_f8f6f4 v[34:37], v[240:247], v[216:223], v[34:37], v193, v193 op_sel_hi:[0,0,0]
	v_mfma_scale_f32_16x16x128_f8f6f4 v[22:25], v[232:239], v[224:231], v[22:25], v193, v193 op_sel_hi:[0,0,0]
	v_mfma_scale_f32_16x16x128_f8f6f4 v[18:21], v[240:247], v[224:231], v[18:21], v193, v193 op_sel_hi:[0,0,0]
	s_setprio 0
	s_add_i32 s71, s71, 2
	s_add_u32 s34, s34, 0x100
	s_addc_u32 s35, s35, 0
	s_add_u32 s69, s69, 0x100
	s_addc_u32 s70, s70, 0
	s_cmp_gt_u32 s71, 13
	s_barrier
	s_cbranch_scc0 .LBB0_2368
	s_lshl_b32 s25, s12, 8
	s_nop 15
	s_nop 15
	s_add_i32 s25, s25, s61
	v_mbcnt_lo_u32_b32 v204, -1, 0
	v_mbcnt_hi_u32_b32 v204, -1, v204
	v_bfe_u32 v204, v204, 4, 1
	v_mul_u32_u24_e32 v204, 24, v204
	v_mov_b32_e32 v205, 0
	v_or_b32_e32 v12, s25, v172
	v_cmp_gt_i32_e32 vcc, s60, v12
	v_mov_b32_e32 v3, 0
	v_mov_b32_e32 v2, 1.0
	v_mov_b32_e32 v4, 1.0
	v_mov_b32_e32 v5, 0
	v_mov_b32_e32 v6, 1.0
	v_mov_b32_e32 v7, 0
	v_mov_b32_e32 v8, 1.0
	v_mov_b32_e32 v9, 0
	s_and_saveexec_b64 s[12:13], vcc
	s_cbranch_execz .LBB0_2371
	s_bfe_u32 s11, s25, 0x50006
	v_mov_b32_e32 v2, s11
	v_cndmask_b32_e64 v2, v172, v2, s[6:7]
	v_lshlrev_b32_e32 v150, 8, v2
	v_lshl_add_u64 v[6:7], v[154:155], 0, v[150:151]
	global_load_dwordx4 v[2:5], v[6:7], off offset:16
	s_nop 0
	global_load_dwordx4 v[6:9], v[6:7], off

.Lrope_b_1:
	s_or_b64 exec, exec, s[98:99]
	v_mul_f32_e32 v150, v138, v7
	v_fma_f32 v150, v142, v6, -v150
	v_mul_f32_e32 v142, v142, v7
	v_fmac_f32_e32 v142, v138, v6
	v_mul_f32_e32 v138, v139, v9
	v_fma_f32 v138, v143, v8, -v138
	v_mul_f32_e32 v143, v143, v9
	v_fmac_f32_e32 v143, v139, v8
	v_mul_f32_e32 v139, v140, v3
	v_fma_f32 v139, v144, v2, -v139
	v_mul_f32_e32 v144, v144, v3
	s_or_b32 s27, s34, 0x80
	v_fmac_f32_e32 v144, v140, v2
	v_mul_f32_e32 v140, v141, v5
	s_cmpk_gt_i32 s27, 0x7ff
	v_readlane_b32 s78, v250, 22
	v_fma_f32 v140, v145, v4, -v140
	v_mul_f32_e32 v145, v145, v5
	v_cvt_pk_bf16_f32 v138, v150, v138
	v_cvt_pk_bf16_f32 v139, v139, v140
	s_mov_b64 s[10:11], -1
	s_cselect_b64 s[36:37], -1, 0
	s_cmpk_lt_i32 s27, 0x800
	v_add_u32_e32 v150, s34, v152
	v_readlane_b32 s79, v250, 23
	v_fmac_f32_e32 v145, v141, v4
	v_cvt_pk_bf16_f32 v140, v142, v143
	v_cvt_pk_bf16_f32 v141, v144, v145
	s_nop 1
	v_permlane16_swap_b32 v138, v140
	v_permlane16_swap_b32 v139, v141
	v_lshl_add_u64 v[206:207], v[16:17], 0, v[204:205]
	global_store_dwordx4 v[206:207], v[138:141], off
	s_cbranch_scc1 .LBB0_2377
	v_lshl_add_u64 v[14:15], v[150:151], 1, v[14:15]
	v_lshl_add_u64 v[16:17], v[14:15], 0, s[22:23]
	s_mov_b64 s[10:11], 0

.LBB0_2379:
	v_mul_f32_e32 v12, v130, v7
	v_mul_f32_e32 v7, v134, v7
	v_fma_f32 v12, v134, v6, -v12
	v_fmac_f32_e32 v7, v130, v6
	v_mul_f32_e32 v6, v131, v9
	v_mul_f32_e32 v9, v135, v9
	v_fma_f32 v6, v135, v8, -v6
	v_fmac_f32_e32 v9, v131, v8
	v_mul_f32_e32 v8, v132, v3
	v_mul_f32_e32 v13, v136, v3
	v_fma_f32 v8, v136, v2, -v8
	v_fmac_f32_e32 v13, v132, v2
	v_mul_f32_e32 v2, v133, v5
	v_fma_f32 v3, v137, v4, -v2
	v_mul_f32_e32 v5, v137, v5
	v_fmac_f32_e32 v5, v133, v4
	v_cvt_pk_bf16_f32 v2, v12, v6
	v_cvt_pk_bf16_f32 v3, v8, v3
	v_cvt_pk_bf16_f32 v4, v7, v9
	v_cvt_pk_bf16_f32 v5, v13, v5
	s_nop 1
	v_permlane16_swap_b32 v2, v4
	v_permlane16_swap_b32 v3, v5
	v_lshl_add_u64 v[206:207], v[16:17], 0, v[204:205]
	global_store_dwordx4 v[206:207], v[2:5], off
	v_or_b32_e32 v12, s25, v173
	v_ashrrev_i32_e32 v13, 31, v12
	v_lshlrev_b64 v[14:15], 10, v[12:13]
	v_cndmask_b32_e64 v16, 0, 1, s[12:13]
	s_mov_b64 s[38:39], -1
	v_cmp_ne_u32_e64 s[10:11], 1, v16
	s_andn2_b64 vcc, exec, s[12:13]
	v_lshl_add_u64 v[14:15], s[14:15], 0, v[14:15]
	s_cbranch_vccnz .LBB0_2383
	v_mov_b32_e32 v16, v10
	v_mov_b32_e32 v17, v151
	v_lshl_add_u64 v[16:17], v[16:17], 1, v[14:15]
	v_lshl_add_u64 v[16:17], v[16:17], 0, s[20:21]
	s_mov_b64 s[38:39], 0

.LBB0_2385:
	s_waitcnt vmcnt(2)
	v_or_b32_e32 v202, s25, v174
	v_cmp_gt_i32_e32 vcc, s60, v202
	v_mov_b32_e32 v3, 0
	v_mov_b32_e32 v2, 1.0
	v_mov_b32_e32 v4, 1.0
	v_mov_b32_e32 v5, 0
	v_mov_b32_e32 v6, 1.0
	v_mov_b32_e32 v7, 0
	v_mov_b32_e32 v8, 1.0
	v_mov_b32_e32 v9, 0
	s_and_saveexec_b64 s[98:99], vcc
	s_cbranch_execz .Lrope_b_2
	s_bfe_u32 s27, s25, 0x50006
	v_mov_b32_e32 v2, s27
	v_cndmask_b32_e64 v2, v174, v2, s[6:7]
	v_lshlrev_b32_e32 v2, 8, v2
	v_mov_b32_e32 v3, v151
	v_lshl_add_u64 v[6:7], v[154:155], 0, v[2:3]
	global_load_dwordx4 v[2:5], v[6:7], off offset:16
	s_nop 0
	global_load_dwordx4 v[6:9], v[6:7], off
.Lrope_b_2:
	s_or_b64 exec, exec, s[98:99]
	v_mul_f32_e32 v130, v122, v199
	v_fma_f32 v130, v126, v198, -v130
	v_mul_f32_e32 v126, v126, v199
	v_fmac_f32_e32 v126, v122, v198
	v_mul_f32_e32 v122, v123, v201
	v_fma_f32 v122, v127, v200, -v122
	v_mul_f32_e32 v127, v127, v201
	v_fmac_f32_e32 v127, v123, v200
	v_mul_f32_e32 v123, v124, v195
	v_fma_f32 v123, v128, v194, -v123
	v_mul_f32_e32 v128, v128, v195
	v_fmac_f32_e32 v128, v124, v194
	v_mul_f32_e32 v124, v125, v197
	v_fma_f32 v124, v129, v196, -v124
	v_mul_f32_e32 v129, v129, v197
	v_cvt_pk_bf16_f32 v122, v130, v122
	v_cvt_pk_bf16_f32 v123, v123, v124
	v_fmac_f32_e32 v129, v125, v196
	v_cvt_pk_bf16_f32 v124, v126, v127
	v_cvt_pk_bf16_f32 v125, v128, v129
	s_nop 1
	v_permlane16_swap_b32 v122, v124
	v_permlane16_swap_b32 v123, v125
	v_lshl_add_u64 v[206:207], v[16:17], 0, v[204:205]
	global_store_dwordx4 v[206:207], v[122:125], off
	v_cndmask_b32_e64 v16, 0, 1, s[36:37]
	v_cmp_ne_u32_e64 s[12:13], 1, v16
	s_andn2_b64 vcc, exec, s[36:37]
	s_mov_b64 s[36:37], -1
	s_cbranch_vccnz .LBB0_2387
	v_lshl_add_u64 v[14:15], v[150:151], 1, v[14:15]
	v_lshl_add_u64 v[16:17], v[14:15], 0, s[22:23]
	s_mov_b64 s[36:37], 0

.LBB0_2389:
	v_mul_f32_e32 v12, v114, v199
	v_mul_f32_e32 v199, v118, v199
	v_fma_f32 v12, v118, v198, -v12
	v_fmac_f32_e32 v199, v114, v198
	v_mul_f32_e32 v198, v115, v201
	v_mul_f32_e32 v201, v119, v201
	v_fma_f32 v198, v119, v200, -v198
	v_fmac_f32_e32 v201, v115, v200
	v_mul_f32_e32 v200, v116, v195
	v_mul_f32_e32 v13, v120, v195
	v_fma_f32 v200, v120, v194, -v200
	v_fmac_f32_e32 v13, v116, v194
	v_mul_f32_e32 v194, v117, v197
	v_fma_f32 v195, v121, v196, -v194
	v_mul_f32_e32 v197, v121, v197
	v_fmac_f32_e32 v197, v117, v196
	v_cvt_pk_bf16_f32 v194, v12, v198
	v_cvt_pk_bf16_f32 v195, v200, v195
	v_cvt_pk_bf16_f32 v196, v199, v201
	v_cvt_pk_bf16_f32 v197, v13, v197
	s_nop 1
	v_permlane16_swap_b32 v194, v196
	v_permlane16_swap_b32 v195, v197
	v_lshl_add_u64 v[206:207], v[16:17], 0, v[204:205]
	global_store_dwordx4 v[206:207], v[194:197], off
	v_or_b32_e32 v12, s25, v174
	v_ashrrev_i32_e32 v13, 31, v12
	v_lshlrev_b64 v[14:15], 10, v[12:13]
	s_mov_b64 s[36:37], -1
	s_and_b64 vcc, exec, s[10:11]
	v_lshl_add_u64 v[14:15], s[14:15], 0, v[14:15]
	s_cbranch_vccnz .LBB0_2393
	v_mov_b32_e32 v16, v10
	v_mov_b32_e32 v17, v151
	v_lshl_add_u64 v[16:17], v[16:17], 1, v[14:15]
	v_lshl_add_u64 v[16:17], v[16:17], 0, s[20:21]
	s_mov_b64 s[36:37], 0

.LBB0_2395:
	s_waitcnt vmcnt(2)
	v_or_b32_e32 v202, s25, v175
	v_cmp_gt_i32_e32 vcc, s60, v202
	v_mov_b32_e32 v195, 0
	v_mov_b32_e32 v194, 1.0
	v_mov_b32_e32 v196, 1.0
	v_mov_b32_e32 v197, 0
	v_mov_b32_e32 v198, 1.0
	v_mov_b32_e32 v199, 0
	v_mov_b32_e32 v200, 1.0
	v_mov_b32_e32 v201, 0
	s_and_saveexec_b64 s[98:99], vcc
	s_cbranch_execz .Lrope_b_3
	s_bfe_u32 s27, s25, 0x50006
	v_mov_b32_e32 v194, s27
	v_cndmask_b32_e64 v194, v175, v194, s[6:7]
	v_lshlrev_b32_e32 v194, 8, v194
	v_mov_b32_e32 v195, v151
	v_lshl_add_u64 v[198:199], v[154:155], 0, v[194:195]
	global_load_dwordx4 v[194:197], v[198:199], off offset:16
	s_nop 0
	global_load_dwordx4 v[198:201], v[198:199], off
.Lrope_b_3:
	s_or_b64 exec, exec, s[98:99]
	v_mul_f32_e32 v114, v106, v7
	v_fma_f32 v114, v110, v6, -v114
	v_mul_f32_e32 v110, v110, v7
	v_fmac_f32_e32 v110, v106, v6
	v_mul_f32_e32 v106, v107, v9
	v_fma_f32 v106, v111, v8, -v106
	v_mul_f32_e32 v111, v111, v9
	v_fmac_f32_e32 v111, v107, v8
	v_mul_f32_e32 v107, v108, v3
	v_fma_f32 v107, v112, v2, -v107
	v_mul_f32_e32 v112, v112, v3
	v_fmac_f32_e32 v112, v108, v2
	v_mul_f32_e32 v108, v109, v5
	v_fma_f32 v108, v113, v4, -v108
	v_mul_f32_e32 v113, v113, v5
	v_cvt_pk_bf16_f32 v106, v114, v106
	v_cvt_pk_bf16_f32 v107, v107, v108
	s_and_b64 vcc, exec, s[12:13]
	s_mov_b64 s[36:37], -1
	v_fmac_f32_e32 v113, v109, v4
	v_cvt_pk_bf16_f32 v108, v110, v111
	v_cvt_pk_bf16_f32 v109, v112, v113
	s_nop 1
	v_permlane16_swap_b32 v106, v108
	v_permlane16_swap_b32 v107, v109
	v_lshl_add_u64 v[206:207], v[16:17], 0, v[204:205]
	global_store_dwordx4 v[206:207], v[106:109], off
	s_cbranch_vccnz .LBB0_2397
	v_lshl_add_u64 v[14:15], v[150:151], 1, v[14:15]
	v_lshl_add_u64 v[16:17], v[14:15], 0, s[22:23]
	s_mov_b64 s[36:37], 0

.LBB0_2399:
	v_mul_f32_e32 v12, v98, v7
	v_mul_f32_e32 v7, v102, v7
	v_fma_f32 v12, v102, v6, -v12
	v_fmac_f32_e32 v7, v98, v6
	v_mul_f32_e32 v6, v99, v9
	v_mul_f32_e32 v9, v103, v9
	v_fma_f32 v6, v103, v8, -v6
	v_fmac_f32_e32 v9, v99, v8
	v_mul_f32_e32 v8, v100, v3
	v_mul_f32_e32 v13, v104, v3
	v_fma_f32 v8, v104, v2, -v8
	v_fmac_f32_e32 v13, v100, v2
	v_mul_f32_e32 v2, v101, v5
	v_fma_f32 v3, v105, v4, -v2
	v_mul_f32_e32 v5, v105, v5
	v_fmac_f32_e32 v5, v101, v4
	v_cvt_pk_bf16_f32 v2, v12, v6
	v_cvt_pk_bf16_f32 v3, v8, v3
	v_cvt_pk_bf16_f32 v4, v7, v9
	v_cvt_pk_bf16_f32 v5, v13, v5
	s_nop 1
	v_permlane16_swap_b32 v2, v4
	v_permlane16_swap_b32 v3, v5
	v_lshl_add_u64 v[206:207], v[16:17], 0, v[204:205]
	global_store_dwordx4 v[206:207], v[2:5], off
	v_or_b32_e32 v12, s25, v175
	v_ashrrev_i32_e32 v13, 31, v12
	v_lshlrev_b64 v[14:15], 10, v[12:13]
	s_mov_b64 s[36:37], -1
	s_and_b64 vcc, exec, s[10:11]
	v_lshl_add_u64 v[14:15], s[14:15], 0, v[14:15]
	s_cbranch_vccnz .LBB0_2403
	v_mov_b32_e32 v16, v10
	v_mov_b32_e32 v17, v151
	v_lshl_add_u64 v[16:17], v[16:17], 1, v[14:15]
	v_lshl_add_u64 v[16:17], v[16:17], 0, s[20:21]
	s_mov_b64 s[36:37], 0

.LBB0_2405:
	s_waitcnt vmcnt(2)
	s_add_i32 s100, s25, 0x80
	v_or_b32_e32 v202, s100, v172
	v_cmp_gt_i32_e32 vcc, s60, v202
	v_mov_b32_e32 v3, 0
	v_mov_b32_e32 v2, 1.0
	v_mov_b32_e32 v4, 1.0
	v_mov_b32_e32 v5, 0
	v_mov_b32_e32 v6, 1.0
	v_mov_b32_e32 v7, 0
	v_mov_b32_e32 v8, 1.0
	v_mov_b32_e32 v9, 0
	s_and_saveexec_b64 s[98:99], vcc
	s_cbranch_execz .Lrope_b_4
	s_bfe_u32 s27, s100, 0x50006
	v_mov_b32_e32 v2, s27
	v_cndmask_b32_e64 v2, v172, v2, s[6:7]
	v_lshlrev_b32_e32 v2, 8, v2
	v_mov_b32_e32 v3, v151
	v_lshl_add_u64 v[6:7], v[154:155], 0, v[2:3]
	global_load_dwordx4 v[2:5], v[6:7], off offset:16
	s_nop 0
	global_load_dwordx4 v[6:9], v[6:7], off
.Lrope_b_4:
	s_or_b64 exec, exec, s[98:99]
	v_mul_f32_e32 v98, v90, v199
	v_fma_f32 v98, v94, v198, -v98
	v_mul_f32_e32 v94, v94, v199
	v_fmac_f32_e32 v94, v90, v198
	v_mul_f32_e32 v90, v91, v201
	v_fma_f32 v90, v95, v200, -v90
	v_mul_f32_e32 v95, v95, v201
	v_fmac_f32_e32 v95, v91, v200
	v_mul_f32_e32 v91, v92, v195
	v_fma_f32 v91, v96, v194, -v91
	v_mul_f32_e32 v96, v96, v195
	v_fmac_f32_e32 v96, v92, v194
	v_mul_f32_e32 v92, v93, v197
	v_fma_f32 v92, v97, v196, -v92
	v_mul_f32_e32 v97, v97, v197
	v_cvt_pk_bf16_f32 v90, v98, v90
	v_cvt_pk_bf16_f32 v91, v91, v92
	s_and_b64 vcc, exec, s[12:13]
	s_mov_b64 s[36:37], -1
	v_fmac_f32_e32 v97, v93, v196
	v_cvt_pk_bf16_f32 v92, v94, v95
	v_cvt_pk_bf16_f32 v93, v96, v97
	s_nop 1
	v_permlane16_swap_b32 v90, v92
	v_permlane16_swap_b32 v91, v93
	v_lshl_add_u64 v[206:207], v[16:17], 0, v[204:205]
	global_store_dwordx4 v[206:207], v[90:93], off
	s_cbranch_vccnz .LBB0_2407
	v_lshl_add_u64 v[14:15], v[150:151], 1, v[14:15]
	v_lshl_add_u64 v[16:17], v[14:15], 0, s[22:23]
	s_mov_b64 s[36:37], 0

.LBB0_2409:
	v_mul_f32_e32 v12, v82, v199
	v_mul_f32_e32 v199, v86, v199
	v_fma_f32 v12, v86, v198, -v12
	v_fmac_f32_e32 v199, v82, v198
	v_mul_f32_e32 v198, v83, v201
	v_mul_f32_e32 v201, v87, v201
	v_fma_f32 v198, v87, v200, -v198
	v_fmac_f32_e32 v201, v83, v200
	v_mul_f32_e32 v200, v84, v195
	v_mul_f32_e32 v13, v88, v195
	v_fma_f32 v200, v88, v194, -v200
	v_fmac_f32_e32 v13, v84, v194
	v_mul_f32_e32 v194, v85, v197
	v_fma_f32 v195, v89, v196, -v194
	v_mul_f32_e32 v197, v89, v197
	v_fmac_f32_e32 v197, v85, v196
	v_cvt_pk_bf16_f32 v194, v12, v198
	v_cvt_pk_bf16_f32 v195, v200, v195
	v_cvt_pk_bf16_f32 v196, v199, v201
	v_cvt_pk_bf16_f32 v197, v13, v197
	s_nop 1
	v_permlane16_swap_b32 v194, v196
	v_permlane16_swap_b32 v195, v197
	v_lshl_add_u64 v[206:207], v[16:17], 0, v[204:205]
	global_store_dwordx4 v[206:207], v[194:197], off
	s_addk_i32 s25, 0x80
	v_or_b32_e32 v12, s25, v172
	v_ashrrev_i32_e32 v13, 31, v12
	v_lshlrev_b64 v[14:15], 10, v[12:13]
	s_mov_b64 s[36:37], -1
	s_and_b64 vcc, exec, s[10:11]
	v_lshl_add_u64 v[14:15], s[14:15], 0, v[14:15]
	s_cbranch_vccnz .LBB0_2413
	v_mov_b32_e32 v16, v10
	v_mov_b32_e32 v17, v151
	v_lshl_add_u64 v[16:17], v[16:17], 1, v[14:15]
	v_lshl_add_u64 v[16:17], v[16:17], 0, s[20:21]
	s_mov_b64 s[36:37], 0

.LBB0_2415:
	s_waitcnt vmcnt(2)
	v_or_b32_e32 v202, s25, v173
	v_cmp_gt_i32_e32 vcc, s60, v202
	v_mov_b32_e32 v195, 0
	v_mov_b32_e32 v194, 1.0
	v_mov_b32_e32 v196, 1.0
	v_mov_b32_e32 v197, 0
	v_mov_b32_e32 v198, 1.0
	v_mov_b32_e32 v199, 0
	v_mov_b32_e32 v200, 1.0
	v_mov_b32_e32 v201, 0
	s_and_saveexec_b64 s[98:99], vcc
	s_cbranch_execz .Lrope_b_5
	s_bfe_u32 s27, s25, 0x50006
	v_mov_b32_e32 v194, s27
	v_cndmask_b32_e64 v194, v173, v194, s[6:7]
	v_lshlrev_b32_e32 v194, 8, v194
	v_mov_b32_e32 v195, v151
	v_lshl_add_u64 v[198:199], v[154:155], 0, v[194:195]
	global_load_dwordx4 v[194:197], v[198:199], off offset:16
	s_nop 0
	global_load_dwordx4 v[198:201], v[198:199], off
.Lrope_b_5:
	s_or_b64 exec, exec, s[98:99]
	v_mul_f32_e32 v82, v74, v7
	v_fma_f32 v82, v78, v6, -v82
	v_mul_f32_e32 v78, v78, v7
	v_fmac_f32_e32 v78, v74, v6
	v_mul_f32_e32 v74, v75, v9
	v_fma_f32 v74, v79, v8, -v74
	v_mul_f32_e32 v79, v79, v9
	v_fmac_f32_e32 v79, v75, v8
	v_mul_f32_e32 v75, v76, v3
	v_fma_f32 v75, v80, v2, -v75
	v_mul_f32_e32 v80, v80, v3
	v_fmac_f32_e32 v80, v76, v2
	v_mul_f32_e32 v76, v77, v5
	v_fma_f32 v76, v81, v4, -v76
	v_mul_f32_e32 v81, v81, v5
	v_cvt_pk_bf16_f32 v74, v82, v74
	v_cvt_pk_bf16_f32 v75, v75, v76
	s_and_b64 vcc, exec, s[12:13]
	s_mov_b64 s[36:37], -1
	v_fmac_f32_e32 v81, v77, v4
	v_cvt_pk_bf16_f32 v76, v78, v79
	v_cvt_pk_bf16_f32 v77, v80, v81
	s_nop 1
	v_permlane16_swap_b32 v74, v76
	v_permlane16_swap_b32 v75, v77
	v_lshl_add_u64 v[206:207], v[16:17], 0, v[204:205]
	global_store_dwordx4 v[206:207], v[74:77], off
	s_cbranch_vccnz .LBB0_2417
	v_lshl_add_u64 v[14:15], v[150:151], 1, v[14:15]
	v_lshl_add_u64 v[16:17], v[14:15], 0, s[22:23]
	s_mov_b64 s[36:37], 0

.LBB0_2419:
	v_mul_f32_e32 v12, v66, v7
	v_mul_f32_e32 v7, v70, v7
	v_fma_f32 v12, v70, v6, -v12
	v_fmac_f32_e32 v7, v66, v6
	v_mul_f32_e32 v6, v67, v9
	v_mul_f32_e32 v9, v71, v9
	v_fma_f32 v6, v71, v8, -v6
	v_fmac_f32_e32 v9, v67, v8
	v_mul_f32_e32 v8, v68, v3
	v_mul_f32_e32 v13, v72, v3
	v_fma_f32 v8, v72, v2, -v8
	v_fmac_f32_e32 v13, v68, v2
	v_mul_f32_e32 v2, v69, v5
	v_fma_f32 v3, v73, v4, -v2
	v_mul_f32_e32 v5, v73, v5
	v_fmac_f32_e32 v5, v69, v4
	v_cvt_pk_bf16_f32 v2, v12, v6
	v_cvt_pk_bf16_f32 v3, v8, v3
	v_cvt_pk_bf16_f32 v4, v7, v9
	v_cvt_pk_bf16_f32 v5, v13, v5
	s_nop 1
	v_permlane16_swap_b32 v2, v4
	v_permlane16_swap_b32 v3, v5
	v_lshl_add_u64 v[206:207], v[16:17], 0, v[204:205]
	global_store_dwordx4 v[206:207], v[2:5], off
	v_or_b32_e32 v12, s25, v173
	v_ashrrev_i32_e32 v13, 31, v12
	v_lshlrev_b64 v[14:15], 10, v[12:13]
	s_mov_b64 s[36:37], -1
	s_and_b64 vcc, exec, s[10:11]
	v_lshl_add_u64 v[14:15], s[14:15], 0, v[14:15]
	s_cbranch_vccnz .LBB0_2423
	v_mov_b32_e32 v16, v10
	v_mov_b32_e32 v17, v151
	v_lshl_add_u64 v[16:17], v[16:17], 1, v[14:15]
	v_lshl_add_u64 v[16:17], v[16:17], 0, s[20:21]
	s_mov_b64 s[36:37], 0

.Lrope_b_6:
	s_or_b64 exec, exec, s[98:99]
	v_mul_f32_e32 v66, v58, v199
	v_fma_f32 v66, v62, v198, -v66
	v_mul_f32_e32 v62, v62, v199
	v_fmac_f32_e32 v62, v58, v198
	v_mul_f32_e32 v58, v59, v201
	v_fma_f32 v58, v63, v200, -v58
	v_mul_f32_e32 v63, v63, v201
	v_fmac_f32_e32 v63, v59, v200
	v_mul_f32_e32 v59, v60, v195
	v_fma_f32 v59, v64, v194, -v59
	v_mul_f32_e32 v64, v64, v195
	v_fmac_f32_e32 v64, v60, v194
	v_mul_f32_e32 v60, v61, v197
	v_fma_f32 v60, v65, v196, -v60
	v_mul_f32_e32 v65, v65, v197
	v_cvt_pk_bf16_f32 v58, v66, v58
	v_cvt_pk_bf16_f32 v59, v59, v60
	s_and_b64 vcc, exec, s[12:13]
	s_mov_b64 s[36:37], -1
	v_fmac_f32_e32 v65, v61, v196
	v_cvt_pk_bf16_f32 v60, v62, v63
	v_cvt_pk_bf16_f32 v61, v64, v65
	s_nop 1
	v_permlane16_swap_b32 v58, v60
	v_permlane16_swap_b32 v59, v61
	v_lshl_add_u64 v[206:207], v[16:17], 0, v[204:205]
	global_store_dwordx4 v[206:207], v[58:61], off
	s_cbranch_vccnz .LBB0_2427
	v_lshl_add_u64 v[14:15], v[150:151], 1, v[14:15]
	v_lshl_add_u64 v[16:17], v[14:15], 0, s[22:23]
	s_mov_b64 s[36:37], 0

.LBB0_2429:
	v_mul_f32_e32 v12, v50, v199
	v_mul_f32_e32 v199, v54, v199
	v_fma_f32 v12, v54, v198, -v12
	v_fmac_f32_e32 v199, v50, v198
	v_mul_f32_e32 v198, v51, v201
	v_mul_f32_e32 v201, v55, v201
	v_fma_f32 v198, v55, v200, -v198
	v_fmac_f32_e32 v201, v51, v200
	v_mul_f32_e32 v200, v52, v195
	v_mul_f32_e32 v13, v56, v195
	v_fma_f32 v200, v56, v194, -v200
	v_fmac_f32_e32 v13, v52, v194
	v_mul_f32_e32 v194, v53, v197
	v_fma_f32 v195, v57, v196, -v194
	v_mul_f32_e32 v197, v57, v197
	v_fmac_f32_e32 v197, v53, v196
	v_cvt_pk_bf16_f32 v194, v12, v198
	v_cvt_pk_bf16_f32 v195, v200, v195
	v_cvt_pk_bf16_f32 v196, v199, v201
	v_cvt_pk_bf16_f32 v197, v13, v197
	s_nop 1
	v_permlane16_swap_b32 v194, v196
	v_permlane16_swap_b32 v195, v197
	v_lshl_add_u64 v[206:207], v[16:17], 0, v[204:205]
	global_store_dwordx4 v[206:207], v[194:197], off
	v_or_b32_e32 v12, s25, v174
	v_ashrrev_i32_e32 v13, 31, v12
	v_lshlrev_b64 v[14:15], 10, v[12:13]
	s_mov_b64 s[36:37], -1
	s_and_b64 vcc, exec, s[10:11]
	v_lshl_add_u64 v[14:15], s[14:15], 0, v[14:15]
	s_cbranch_vccnz .LBB0_2433
	v_mov_b32_e32 v16, v10
	v_mov_b32_e32 v17, v151
	v_lshl_add_u64 v[16:17], v[16:17], 1, v[14:15]
	v_lshl_add_u64 v[16:17], v[16:17], 0, s[20:21]
	s_mov_b64 s[36:37], 0

.LBB0_2435:
	s_waitcnt vmcnt(2)
	v_mul_f32_e32 v50, v42, v7
	v_fma_f32 v50, v46, v6, -v50
	v_mul_f32_e32 v46, v46, v7
	v_fmac_f32_e32 v46, v42, v6
	v_mul_f32_e32 v42, v43, v9
	v_fma_f32 v42, v47, v8, -v42
	v_mul_f32_e32 v47, v47, v9
	v_fmac_f32_e32 v47, v43, v8
	v_mul_f32_e32 v43, v44, v3
	v_fma_f32 v43, v48, v2, -v43
	v_mul_f32_e32 v48, v48, v3
	v_fmac_f32_e32 v48, v44, v2
	v_mul_f32_e32 v44, v45, v5
	v_fma_f32 v44, v49, v4, -v44
	v_mul_f32_e32 v49, v49, v5
	v_cvt_pk_bf16_f32 v42, v50, v42
	v_cvt_pk_bf16_f32 v43, v43, v44
	s_and_b64 vcc, exec, s[12:13]
	s_mov_b64 s[36:37], -1
	v_fmac_f32_e32 v49, v45, v4
	v_cvt_pk_bf16_f32 v44, v46, v47
	v_cvt_pk_bf16_f32 v45, v48, v49
	s_nop 1
	v_permlane16_swap_b32 v42, v44
	v_permlane16_swap_b32 v43, v45
	v_lshl_add_u64 v[206:207], v[16:17], 0, v[204:205]
	global_store_dwordx4 v[206:207], v[42:45], off
	s_cbranch_vccnz .LBB0_2437
	v_lshl_add_u64 v[14:15], v[150:151], 1, v[14:15]
	v_lshl_add_u64 v[16:17], v[14:15], 0, s[22:23]
	s_mov_b64 s[36:37], 0

.LBB0_2439:
	v_mul_f32_e32 v12, v34, v7
	v_mul_f32_e32 v7, v38, v7
	v_fma_f32 v12, v38, v6, -v12
	v_fmac_f32_e32 v7, v34, v6
	v_mul_f32_e32 v6, v35, v9
	v_mul_f32_e32 v9, v39, v9
	v_fma_f32 v6, v39, v8, -v6
	v_fmac_f32_e32 v9, v35, v8
	v_mul_f32_e32 v8, v36, v3
	v_mul_f32_e32 v13, v40, v3
	v_fma_f32 v8, v40, v2, -v8
	v_fmac_f32_e32 v13, v36, v2
	v_mul_f32_e32 v2, v37, v5
	v_fma_f32 v3, v41, v4, -v2
	v_mul_f32_e32 v5, v41, v5
	v_fmac_f32_e32 v5, v37, v4
	v_cvt_pk_bf16_f32 v2, v12, v6
	v_cvt_pk_bf16_f32 v3, v8, v3
	v_cvt_pk_bf16_f32 v4, v7, v9
	v_cvt_pk_bf16_f32 v5, v13, v5
	s_nop 1
	v_permlane16_swap_b32 v2, v4
	v_permlane16_swap_b32 v3, v5
	v_lshl_add_u64 v[206:207], v[16:17], 0, v[204:205]
	global_store_dwordx4 v[206:207], v[2:5], off
	v_or_b32_e32 v12, s25, v175
	v_cmp_gt_i32_e32 vcc, s60, v12
	v_mov_b32_e32 v7, 0
	v_mov_b32_e32 v6, 1.0
	v_mov_b32_e32 v8, 1.0
	v_mov_b32_e32 v9, 0
	v_mov_b32_e32 v2, 1.0
	v_mov_b32_e32 v3, 0
	v_mov_b32_e32 v4, 1.0
	v_mov_b32_e32 v5, 0
	s_and_saveexec_b64 s[36:37], vcc
	s_cbranch_execz .LBB0_2441
	s_bfe_u32 s25, s25, 0x50006
	v_mov_b32_e32 v2, s25
	v_cndmask_b32_e64 v2, v175, v2, s[6:7]
	v_lshlrev_b32_e32 v2, 8, v2
	v_mov_b32_e32 v3, v151
	v_lshl_add_u64 v[2:3], v[154:155], 0, v[2:3]
	global_load_dwordx4 v[6:9], v[2:3], off offset:16
	s_nop 0
	global_load_dwordx4 v[2:5], v[2:3], off
